# static s_setprio 1 for waves 4-7 (younger half), on top of LRU conv/weight load batching + stage_rstd batching + convert fixes
# speedup vs baseline: 1.0201x; 1.0060x over previous
.LBB0_3:
	s_load_dwordx2 s[74:75], s[0:1], 0x110
	s_load_dwordx4 s[88:91], s[0:1], 0x100
	s_load_dwordx16 s[36:51], s[0:1], 0x0
	s_load_dwordx16 s[4:19], s[0:1], 0x40
	s_lshl_b32 s70, s72, 1
	v_lshrrev_b32_e32 v1, 20, v0
	v_lshrrev_b32_e32 v0, 10, v0
	v_or_b32_e32 v0, v0, v1
	s_waitcnt lgkmcnt(0)
	v_writelane_b32 v254, s4, 6
	s_movk_i32 s73, 0x3ff
	v_and_or_b32 v0, v0, s73, v190
	v_writelane_b32 v254, s5, 7
	v_writelane_b32 v254, s6, 8
	v_writelane_b32 v254, s7, 9
	v_writelane_b32 v254, s8, 10
	v_writelane_b32 v254, s9, 11
	v_writelane_b32 v254, s10, 12
	v_writelane_b32 v254, s11, 13
	v_writelane_b32 v254, s12, 14
	v_writelane_b32 v254, s13, 15
	v_writelane_b32 v254, s14, 16
	v_writelane_b32 v254, s15, 17
	v_writelane_b32 v254, s16, 18
	v_writelane_b32 v254, s17, 19
	v_writelane_b32 v254, s18, 20
	v_writelane_b32 v254, s19, 21
	s_load_dwordx16 s[4:19], s[0:1], 0x80
	v_cmp_eq_u32_e64 s[2:3], 0, v0
	v_and_b32_e32 v191, 0xff, v190
	s_movk_i32 s71, 0x100
	v_mov_b32_e32 v145, 0
	s_waitcnt lgkmcnt(0)
	v_writelane_b32 v254, s4, 22
	s_mov_b32 s69, 0xfffc0000
	v_mov_b32_e32 v192, 0x358637bd
	v_writelane_b32 v254, s5, 23
	v_writelane_b32 v254, s6, 24
	v_writelane_b32 v254, s7, 25
	v_writelane_b32 v254, s8, 26
	v_writelane_b32 v254, s9, 27
	v_writelane_b32 v254, s10, 28
	v_writelane_b32 v254, s11, 29
	v_writelane_b32 v254, s12, 30
	v_writelane_b32 v254, s13, 31
	v_writelane_b32 v254, s14, 32
	v_writelane_b32 v254, s15, 33
	v_writelane_b32 v254, s16, 34
	v_writelane_b32 v254, s17, 35
	v_writelane_b32 v254, s18, 36
	v_writelane_b32 v254, s19, 37
	s_load_dwordx16 s[4:19], s[0:1], 0xc0
	s_lshl_b32 s0, s79, 1
	s_movk_i32 s85, 0x5800
	s_mov_b32 s81, 0x10000
	s_mov_b32 s78, 0x20000
	s_waitcnt lgkmcnt(0)
	v_writelane_b32 v254, s4, 38
	s_movk_i32 s33, 0x1600
	s_movk_i32 s83, 0x7fff
	v_writelane_b32 v254, s5, 39
	v_writelane_b32 v254, s6, 40
	v_writelane_b32 v254, s7, 41
	v_writelane_b32 v254, s8, 42
	v_writelane_b32 v254, s9, 43
	v_writelane_b32 v254, s10, 44
	v_writelane_b32 v254, s11, 45
	v_writelane_b32 v254, s12, 46
	v_writelane_b32 v254, s13, 47
	v_writelane_b32 v254, s14, 48
	v_writelane_b32 v254, s15, 49
	v_writelane_b32 v254, s16, 50
	v_writelane_b32 v254, s17, 51
	v_writelane_b32 v254, s18, 52
	v_writelane_b32 v254, s19, 53
	s_lshl_b32 s4, s72, 3
	s_cmpk_lt_i32 s79, 0x100
	v_writelane_b32 v254, s0, 54
	s_cselect_b64 s[0:1], -1, 0
	v_writelane_b32 v254, s0, 55
	s_cmpk_lt_i32 s79, 0x200
	v_mov_b32_e32 v193, 0x3ecc95a3
	v_writelane_b32 v254, s1, 56
	s_cselect_b64 s[0:1], -1, 0
	v_writelane_b32 v254, s0, 57
	s_mov_b32 s82, 0x3db8aa3b
	s_mov_b64 s[86:87], 0x20000
	v_writelane_b32 v254, s1, 58
	s_add_i32 s0, s70, 0xbff
	v_writelane_b32 v254, s0, 59
	s_add_i32 s0, s70, 0x9ff
	s_cmpk_lt_i32 s79, 0x5c0
	v_writelane_b32 v254, s0, 60
	s_cselect_b64 s[0:1], -1, 0
	v_writelane_b32 v254, s0, 61
	s_ashr_i32 s5, s4, 31
	s_mov_b64 s[10:11], 0x80
	v_writelane_b32 v254, s1, 62
	v_cmp_gt_u32_e64 s[0:1], 64, v190
	s_mov_b64 s[92:93], 0x40080
	s_mov_b64 s[94:95], 0x60080
	v_writelane_b32 v254, s0, 63
	s_mov_b32 s76, 0x3e38aa3b
	v_mov_b32_e32 v195, 0x3c088889
	v_writelane_b32 v255, s1, 0
	v_writelane_b32 v255, s2, 1
	s_bfe_i32 s0, s72, 0x1001e
	s_mov_b32 s1, 0
	v_writelane_b32 v255, s3, 2
	v_writelane_b32 v255, s0, 3
	s_abs_i32 s0, s70
	v_cvt_f32_u32_e32 v0, s0
	v_writelane_b32 v255, s0, 4
	s_sub_i32 s0, 0, s0
	s_mov_b32 s84, 0xbe800000
	v_rcp_iflag_f32_e32 v0, v0
	v_mov_b32_e32 v197, 0x3c0881c4
	v_mov_b32_e32 v198, 0xbab64f3b
	v_mov_b32_e32 v200, 0x21004
	v_mul_f32_e32 v0, 0x4f7ffffe, v0
	v_cvt_u32_f32_e32 v0, v0
	v_mov_b32_e32 v201, 1
	v_mov_b64_e32 v[252:253], 0x40000
	v_mov_b32_e32 v202, 0x7f800000
	v_readfirstlane_b32 s2, v0
	s_mul_i32 s0, s0, s2
	s_mul_hi_u32 s0, s2, s0
	s_add_i32 s0, s2, s0
	v_writelane_b32 v255, s0, 5
	v_writelane_b32 v255, s4, 6
	s_lshl_b64 s[2:3], s[4:5], 2
	v_mov_b32_e32 v150, 0x3f317218
	v_writelane_b32 v255, s5, 7
	v_writelane_b32 v255, s2, 8
	v_mbcnt_lo_u32_b32 v0, -1, 0
	v_mbcnt_hi_u32_b32 v194, -1, v0
	v_writelane_b32 v255, s3, 9
	s_add_u32 s2, s90, 0xc00
	s_addc_u32 s3, s91, 0
	v_writelane_b32 v255, s2, 10
	s_lshl_b32 s0, s79, 9
	v_mov_b32_e32 v203, 2
	v_writelane_b32 v255, s3, 11
	s_lshl_b64 s[2:3], s[4:5], 12
	v_writelane_b32 v255, s2, 12
	v_mov_b32_e32 v204, 0x20000
	v_mov_b32_e32 v205, 0x20800
	v_writelane_b32 v255, s3, 13
	v_writelane_b32 v255, s0, 14
	s_lshl_b32 s0, s72, 9
	v_writelane_b32 v255, s0, 15
	s_lshl_b32 s0, s79, 17
	v_writelane_b32 v255, s0, 16
	s_lshl_b32 s0, s72, 17
	v_writelane_b32 v255, s0, 17
	s_lshl_b32 s0, s79, 3
	v_writelane_b32 v255, s0, 18
	s_lshl_b32 s0, s79, 19
	v_writelane_b32 v255, s0, 19
	s_lshl_b32 s0, s72, 19
	v_writelane_b32 v255, s0, 20
	s_lshl_b64 s[2:3], s[4:5], 11
	v_writelane_b32 v255, s2, 21
	s_mov_b64 s[4:5], 0x20080
	v_mov_b32_e32 v196, 0xfffffe00
	v_writelane_b32 v255, s3, 22
	v_writelane_b32 v255, s72, 23
	v_writelane_b32 v255, s74, 24
	v_readlane_b32 s2, v254, 0
	v_mov_b32_e32 v211, 0x50
	v_writelane_b32 v255, s75, 25
	v_writelane_b32 v255, s70, 26
	v_writelane_b32 v255, s36, 27
	v_mov_b32_e32 v212, 0x60
	v_mov_b32_e32 v199, 0x70
	v_writelane_b32 v255, s37, 28
	v_writelane_b32 v255, s38, 29
	v_writelane_b32 v255, s39, 30
	v_writelane_b32 v255, s40, 31
	v_writelane_b32 v255, s41, 32
	v_writelane_b32 v255, s42, 33
	v_writelane_b32 v255, s43, 34
	v_writelane_b32 v255, s44, 35
	v_writelane_b32 v255, s45, 36
	v_writelane_b32 v255, s46, 37
	v_writelane_b32 v255, s47, 38
	v_writelane_b32 v255, s48, 39
	v_writelane_b32 v255, s49, 40
	v_writelane_b32 v255, s50, 41
	v_mov_b32_e32 v210, 0x160000
	v_not_b32_e32 v213, 63
	v_not_b32_e32 v214, 31
	v_mov_b32_e32 v215, 0x7fc00000
	s_mov_b32 s96, s2
	v_writelane_b32 v255, s51, 42
	v_readfirstlane_b32 s98, v190
	s_nop 3
	s_cmpk_ge_u32 s98, 0x100
	s_cbranch_scc0 .Lprio_done
	s_setprio 1
.Lprio_done:
	v_readlane_b32 s3, v254, 1
	s_branch .LBB0_7

.LBB0_235:
	s_ashr_i32 s8, s30, 5
	s_lshr_b32 s3, s8, 30
	s_add_i32 s9, s8, s3
	s_lshl_b32 s3, s30, 3
	s_and_b32 s3, s3, 56
	s_and_b32 s6, s9, -4
	s_bfe_u32 s2, s30, 0x20003
	s_add_i32 s6, s6, s3
	s_or_b32 s22, s6, s2
	s_lshl_b32 s6, s22, 8
	v_mov_b32_e32 v0, v190
	s_ashr_i32 s7, s6, 31
	s_lshl_b64 s[2:3], s[6:7], 2
	v_ashrrev_i32_e32 v1, 5, v0
	v_and_b32_e32 v2, -8, v1
	s_add_u32 s2, s0, s2
	s_addc_u32 s3, s24, s3
	v_lshlrev_b32_sdwa v144, v203, v0 dst_sel:DWORD dst_unused:UNUSED_PAD src0_sel:DWORD src1_sel:BYTE_0
	v_ashrrev_i32_e32 v3, 31, v2
	v_lshl_add_u64 v[4:5], s[2:3], 0, v[144:145]
	v_lshlrev_b64 v[6:7], 16, v[2:3]
	v_lshl_add_u64 v[8:9], v[4:5], 0, v[6:7]
	s_mov_b64 s[98:99], 0x10000
	v_lshl_add_u64 v[10:11], v[8:9], 0, s[98:99]
	v_lshl_add_u64 v[12:13], v[10:11], 0, s[98:99]
	v_lshl_add_u64 v[14:15], v[12:13], 0, s[98:99]
	v_lshl_add_u64 v[16:17], v[14:15], 0, s[98:99]
	v_lshl_add_u64 v[18:19], v[16:17], 0, s[98:99]
	v_lshl_add_u64 v[20:21], v[18:19], 0, s[98:99]
	v_lshl_add_u64 v[22:23], v[20:21], 0, s[98:99]
	global_load_dword v24, v[8:9], off
	global_load_dword v25, v[10:11], off
	global_load_dword v26, v[12:13], off
	global_load_dword v27, v[14:15], off
	global_load_dword v28, v[16:17], off
	global_load_dword v29, v[18:19], off
	global_load_dword v30, v[20:21], off
	global_load_dword v31, v[22:23], off
	v_cmp_gt_i32_e32 vcc, s71, v0
	s_waitcnt vmcnt(1)
	v_add_f32_e32 v3, 0, v24
	v_add_f32_e32 v3, v3, v25
	v_add_f32_e32 v3, v3, v26
	v_add_f32_e32 v3, v3, v27
	v_add_f32_e32 v3, v3, v28
	v_add_f32_e32 v6, v3, v29
	v_add_f32_e32 v6, v6, v30
	s_waitcnt lgkmcnt(0)
	s_barrier
	s_waitcnt vmcnt(0)
	v_add_f32_e32 v2, v6, v31
	v_lshl_add_u32 v1, v0, 2, v204
	ds_write_b32 v1, v2
	s_waitcnt lgkmcnt(0)
	s_barrier
	s_and_saveexec_b64 s[2:3], vcc
	s_cbranch_execz .LBB0_237
	ds_read2st64_b32 v[2:3], v1 offset1:4
	v_lshl_add_u32 v0, v0, 2, v205
	s_waitcnt lgkmcnt(0)
	v_add_f32_e32 v1, v2, v3
	v_fmamk_f32 v1, v1, 0x3a800000, v192
	v_mul_f32_e32 v2, 0x4b800000, v1
	v_cmp_gt_f32_e32 vcc, s58, v1
	s_nop 1
	v_cndmask_b32_e32 v1, v1, v2, vcc
	v_rsq_f32_e32 v1, v1
	s_nop 0
	v_mul_f32_e32 v2, 0x45800000, v1
	v_cndmask_b32_e32 v1, v1, v2, vcc
	ds_write_b32 v0, v1

.LBB0_296:
	s_mul_i32 s2, s28, s70
	s_add_i32 s2, s2, s27
	s_bfe_u32 s37, s2, 0x60003
	s_mov_b64 s[8:9], s[74:75]
	s_waitcnt lgkmcnt(0)
	s_barrier
	s_lshl_b32 s35, s37, 6
	v_lshlrev_b32_e32 v144, 1, v151
	s_add_i32 s3, s35, -2
	v_lshl_add_u64 v[8:9], s[8:9], 0, v[144:145]
	s_mov_b64 s[8:9], 0x91e0000
	s_ashr_i32 s2, s2, 9
	v_lshl_add_u64 v[48:49], v[8:9], 0, s[8:9]
	v_add_u32_e32 v50, s3, v154
	s_waitcnt vmcnt(0)
	v_mov_b64_e32 v[14:15], v[6:7]
	s_lshl_b32 s36, s2, 12
	v_cmp_gt_u32_e64 s[8:9], s67, v50
	v_mov_b64_e32 v[12:13], v[4:5]
	v_mov_b64_e32 v[10:11], v[2:3]
	v_mov_b64_e32 v[8:9], v[0:1]
	v_mov_b64_e32 v[216:217], 0
	v_mov_b64_e32 v[218:219], 0
	s_and_saveexec_b64 s[12:13], s[8:9]
	v_or_b32_e32 v232, s36, v50
	v_ashrrev_i32_e32 v233, 31, v232
	v_lshlrev_b64 v[232:233], 10, v[232:233]
	v_lshl_add_u64 v[232:233], v[48:49], 0, v[232:233]
	global_load_dwordx4 v[216:219], v[232:233], off
	s_or_b64 exec, exec, s[12:13]
	v_add_u32_e32 v51, 1, v50
	v_cmp_gt_u32_e64 s[8:9], s67, v51
	v_mov_b64_e32 v[220:221], 0
	v_mov_b64_e32 v[222:223], 0
	s_and_saveexec_b64 s[12:13], s[8:9]
	v_or_b32_e32 v234, s36, v51
	v_ashrrev_i32_e32 v235, 31, v234
	v_lshlrev_b64 v[234:235], 10, v[234:235]
	v_lshl_add_u64 v[234:235], v[48:49], 0, v[234:235]
	global_load_dwordx4 v[220:223], v[234:235], off
	s_or_b64 exec, exec, s[12:13]
	v_add_u32_e32 v51, s35, v154
	v_cmp_gt_u32_e64 s[8:9], s67, v51
	v_mov_b64_e32 v[224:225], 0
	v_mov_b64_e32 v[226:227], 0
	s_and_saveexec_b64 s[12:13], s[8:9]
	v_or_b32_e32 v236, s36, v51
	v_ashrrev_i32_e32 v237, 31, v236
	v_lshlrev_b64 v[236:237], 10, v[236:237]
	v_lshl_add_u64 v[236:237], v[48:49], 0, v[236:237]
	global_load_dwordx4 v[224:227], v[236:237], off
	s_or_b64 exec, exec, s[12:13]
	v_add_u32_e32 v50, 3, v50
	v_cmp_gt_u32_e64 s[8:9], s67, v50
	v_mov_b64_e32 v[228:229], 0
	v_mov_b64_e32 v[230:231], 0
	s_and_saveexec_b64 s[12:13], s[8:9]
	v_or_b32_e32 v238, s36, v50
	v_ashrrev_i32_e32 v239, 31, v238
	v_lshlrev_b64 v[238:239], 10, v[238:239]
	v_lshl_add_u64 v[238:239], v[48:49], 0, v[238:239]
	global_load_dwordx4 v[228:231], v[238:239], off
	s_or_b64 exec, exec, s[12:13]
	s_waitcnt vmcnt(0)
	v_lshlrev_b32_e32 v52, 16, v216
	v_and_b32_e32 v53, 0xffff0000, v216
	v_lshlrev_b32_e32 v8, 16, v217
	v_and_b32_e32 v9, 0xffff0000, v217
	v_lshlrev_b32_e32 v12, 16, v218
	v_and_b32_e32 v13, 0xffff0000, v218
	v_lshlrev_b32_e32 v10, 16, v219
	v_and_b32_e32 v11, 0xffff0000, v219
	v_pk_fma_f32 v[14:15], v[22:23], v[10:11], v[6:7]
	v_pk_fma_f32 v[12:13], v[20:21], v[12:13], v[4:5]
	v_pk_fma_f32 v[10:11], v[18:19], v[8:9], v[2:3]
	v_pk_fma_f32 v[8:9], v[16:17], v[52:53], v[0:1]
	v_lshlrev_b32_e32 v56, 16, v220
	v_and_b32_e32 v57, 0xffff0000, v220
	v_lshlrev_b32_e32 v52, 16, v221
	v_and_b32_e32 v53, 0xffff0000, v221
	v_lshlrev_b32_e32 v58, 16, v222
	v_and_b32_e32 v59, 0xffff0000, v222
	v_lshlrev_b32_e32 v54, 16, v223
	v_and_b32_e32 v55, 0xffff0000, v223
	v_pk_fma_f32 v[14:15], v[30:31], v[54:55], v[14:15]
	v_pk_fma_f32 v[12:13], v[28:29], v[58:59], v[12:13]
	v_pk_fma_f32 v[10:11], v[26:27], v[52:53], v[10:11]
	v_pk_fma_f32 v[8:9], v[24:25], v[56:57], v[8:9]
	v_lshlrev_b32_e32 v56, 16, v224
	v_and_b32_e32 v57, 0xffff0000, v224
	v_lshlrev_b32_e32 v52, 16, v225
	v_and_b32_e32 v53, 0xffff0000, v225
	v_lshlrev_b32_e32 v58, 16, v226
	v_and_b32_e32 v59, 0xffff0000, v226
	v_lshlrev_b32_e32 v54, 16, v227
	v_and_b32_e32 v55, 0xffff0000, v227
	v_pk_fma_f32 v[14:15], v[38:39], v[54:55], v[14:15]
	v_pk_fma_f32 v[12:13], v[36:37], v[58:59], v[12:13]
	v_pk_fma_f32 v[10:11], v[34:35], v[52:53], v[10:11]
	v_pk_fma_f32 v[8:9], v[32:33], v[56:57], v[8:9]
	v_lshlrev_b32_e32 v54, 16, v228
	v_and_b32_e32 v55, 0xffff0000, v228
	v_lshlrev_b32_e32 v50, 16, v229
	v_and_b32_e32 v51, 0xffff0000, v229
	v_lshlrev_b32_e32 v56, 16, v230
	v_and_b32_e32 v57, 0xffff0000, v230
	v_lshlrev_b32_e32 v52, 16, v231
	v_and_b32_e32 v53, 0xffff0000, v231
	v_pk_fma_f32 v[14:15], v[46:47], v[52:53], v[14:15]
	v_pk_fma_f32 v[12:13], v[44:45], v[56:57], v[12:13]
	v_pk_fma_f32 v[10:11], v[42:43], v[50:51], v[10:11]
	v_pk_fma_f32 v[8:9], v[40:41], v[54:55], v[8:9]
	v_cvt_pk_bf16_f32 v8, v8, v9
	v_cvt_pk_bf16_f32 v9, v10, v11
	v_cvt_pk_bf16_f32 v10, v12, v13
	v_cvt_pk_bf16_f32 v11, v14, v15
	ds_write_b128 v159, v[8:11]
	v_add_u32_e32 v50, s3, v157
	v_mov_b64_e32 v[14:15], v[6:7]
	v_cmp_gt_u32_e64 s[8:9], s67, v50
	v_mov_b64_e32 v[12:13], v[4:5]
	v_mov_b64_e32 v[10:11], v[2:3]
	v_mov_b64_e32 v[8:9], v[0:1]
	v_mov_b64_e32 v[216:217], 0
	v_mov_b64_e32 v[218:219], 0
	s_and_saveexec_b64 s[12:13], s[8:9]
	v_or_b32_e32 v232, s36, v50
	v_ashrrev_i32_e32 v233, 31, v232
	v_lshlrev_b64 v[232:233], 10, v[232:233]
	v_lshl_add_u64 v[232:233], v[48:49], 0, v[232:233]
	global_load_dwordx4 v[216:219], v[232:233], off
	s_or_b64 exec, exec, s[12:13]
	v_add_u32_e32 v51, 1, v50
	v_cmp_gt_u32_e64 s[8:9], s67, v51
	v_mov_b64_e32 v[220:221], 0
	v_mov_b64_e32 v[222:223], 0
	s_and_saveexec_b64 s[12:13], s[8:9]
	v_or_b32_e32 v234, s36, v51
	v_ashrrev_i32_e32 v235, 31, v234
	v_lshlrev_b64 v[234:235], 10, v[234:235]
	v_lshl_add_u64 v[234:235], v[48:49], 0, v[234:235]
	global_load_dwordx4 v[220:223], v[234:235], off
	s_or_b64 exec, exec, s[12:13]
	v_add_u32_e32 v51, s35, v157
	v_cmp_gt_u32_e64 s[8:9], s67, v51
	v_mov_b64_e32 v[224:225], 0
	v_mov_b64_e32 v[226:227], 0
	s_and_saveexec_b64 s[12:13], s[8:9]
	v_or_b32_e32 v236, s36, v51
	v_ashrrev_i32_e32 v237, 31, v236
	v_lshlrev_b64 v[236:237], 10, v[236:237]
	v_lshl_add_u64 v[236:237], v[48:49], 0, v[236:237]
	global_load_dwordx4 v[224:227], v[236:237], off
	s_or_b64 exec, exec, s[12:13]
	v_add_u32_e32 v50, 3, v50
	v_cmp_gt_u32_e64 s[8:9], s67, v50
	v_mov_b64_e32 v[228:229], 0
	v_mov_b64_e32 v[230:231], 0
	s_and_saveexec_b64 s[12:13], s[8:9]
	v_or_b32_e32 v238, s36, v50
	v_ashrrev_i32_e32 v239, 31, v238
	v_lshlrev_b64 v[238:239], 10, v[238:239]
	v_lshl_add_u64 v[238:239], v[48:49], 0, v[238:239]
	global_load_dwordx4 v[228:231], v[238:239], off
	s_or_b64 exec, exec, s[12:13]
	s_waitcnt vmcnt(0)
	v_lshlrev_b32_e32 v52, 16, v216
	v_and_b32_e32 v53, 0xffff0000, v216
	v_lshlrev_b32_e32 v8, 16, v217
	v_and_b32_e32 v9, 0xffff0000, v217
	v_lshlrev_b32_e32 v12, 16, v218
	v_and_b32_e32 v13, 0xffff0000, v218
	v_lshlrev_b32_e32 v10, 16, v219
	v_and_b32_e32 v11, 0xffff0000, v219
	v_pk_fma_f32 v[14:15], v[22:23], v[10:11], v[6:7]
	v_pk_fma_f32 v[12:13], v[20:21], v[12:13], v[4:5]
	v_pk_fma_f32 v[10:11], v[18:19], v[8:9], v[2:3]
	v_pk_fma_f32 v[8:9], v[16:17], v[52:53], v[0:1]
	v_lshlrev_b32_e32 v56, 16, v220
	v_and_b32_e32 v57, 0xffff0000, v220
	v_lshlrev_b32_e32 v52, 16, v221
	v_and_b32_e32 v53, 0xffff0000, v221
	v_lshlrev_b32_e32 v58, 16, v222
	v_and_b32_e32 v59, 0xffff0000, v222
	v_lshlrev_b32_e32 v54, 16, v223
	v_and_b32_e32 v55, 0xffff0000, v223
	v_pk_fma_f32 v[14:15], v[30:31], v[54:55], v[14:15]
	v_pk_fma_f32 v[12:13], v[28:29], v[58:59], v[12:13]
	v_pk_fma_f32 v[10:11], v[26:27], v[52:53], v[10:11]
	v_pk_fma_f32 v[8:9], v[24:25], v[56:57], v[8:9]
	v_lshlrev_b32_e32 v56, 16, v224
	v_and_b32_e32 v57, 0xffff0000, v224
	v_lshlrev_b32_e32 v52, 16, v225
	v_and_b32_e32 v53, 0xffff0000, v225
	v_lshlrev_b32_e32 v58, 16, v226
	v_and_b32_e32 v59, 0xffff0000, v226
	v_lshlrev_b32_e32 v54, 16, v227
	v_and_b32_e32 v55, 0xffff0000, v227
	v_pk_fma_f32 v[14:15], v[38:39], v[54:55], v[14:15]
	v_pk_fma_f32 v[12:13], v[36:37], v[58:59], v[12:13]
	v_pk_fma_f32 v[10:11], v[34:35], v[52:53], v[10:11]
	v_pk_fma_f32 v[8:9], v[32:33], v[56:57], v[8:9]
	v_lshlrev_b32_e32 v52, 16, v228
	v_and_b32_e32 v53, 0xffff0000, v228
	v_lshlrev_b32_e32 v48, 16, v229
	v_and_b32_e32 v49, 0xffff0000, v229
	v_lshlrev_b32_e32 v54, 16, v230
	v_and_b32_e32 v55, 0xffff0000, v230
	v_lshlrev_b32_e32 v50, 16, v231
	v_and_b32_e32 v51, 0xffff0000, v231
	v_pk_fma_f32 v[14:15], v[46:47], v[50:51], v[14:15]
	v_pk_fma_f32 v[12:13], v[44:45], v[54:55], v[12:13]
	v_pk_fma_f32 v[10:11], v[42:43], v[48:49], v[10:11]
	v_pk_fma_f32 v[8:9], v[40:41], v[52:53], v[8:9]
	s_mov_b64 s[8:9], s[74:75]
	v_cvt_pk_bf16_f32 v8, v8, v9
	v_cvt_pk_bf16_f32 v9, v10, v11
	v_cvt_pk_bf16_f32 v10, v12, v13
	v_cvt_pk_bf16_f32 v11, v14, v15
	ds_write_b128 v160, v[8:11]
	s_lshl_b32 s3, s26, 3
	s_add_u32 s8, s8, s3
	s_addc_u32 s9, s9, 0
	v_mov_b32_e32 v141, v145
	v_lshl_add_u64 v[8:9], s[8:9], 0, v[140:141]
	s_mov_b64 s[8:9], 0x115e0000
	v_lshl_add_u64 v[8:9], v[8:9], 0, s[8:9]
	s_lshl_b32 s12, s2, 1
	v_cmp_ne_u32_e64 s[8:9], s37, v76
	s_and_saveexec_b64 s[2:3], s[8:9]
	s_cbranch_execz .LBB0_328
	v_cmp_le_i32_e64 s[8:9], s37, v76
	v_add_u32_e32 v12, v156, v155
	s_nop 0
	v_cndmask_b32_e64 v10, 0, 1, s[8:9]
	v_or_b32_e32 v10, s12, v10
	v_ashrrev_i32_e32 v11, 31, v10
	v_lshlrev_b64 v[10:11], 18, v[10:11]
	v_lshl_add_u64 v[10:11], v[8:9], 0, v[10:11]
	v_lshl_add_u64 v[10:11], v[10:11], 0, v[78:79]
	flat_load_dwordx2 v[10:11], v[10:11]
	s_waitcnt vmcnt(0) lgkmcnt(0)
	ds_write_b64 v12, v[10:11] offset:8192
	s_or_b64 exec, exec, s[2:3]
	v_cmp_ne_u32_e64 s[8:9], s37, v80
	s_and_saveexec_b64 s[2:3], s[8:9]
	s_cbranch_execnz .LBB0_329

.LBB0_383:
	s_bfe_u32 s25, s0, 0x60003
	s_mov_b64 s[6:7], s[74:75]
	s_waitcnt lgkmcnt(0)
	s_barrier
	s_lshl_b32 s28, s25, 6
	v_lshlrev_b32_e32 v144, 1, v78
	s_add_i32 s29, s28, -2
	v_lshl_add_u64 v[8:9], s[6:7], 0, v[144:145]
	s_mov_b64 s[6:7], 0x91e0000
	s_ashr_i32 s26, s0, 9
	v_lshl_add_u64 v[48:49], v[8:9], 0, s[6:7]
	v_add_u32_e32 v50, s29, v79
	s_waitcnt vmcnt(0)
	v_mov_b64_e32 v[14:15], v[6:7]
	s_lshl_b32 s27, s26, 12
	v_cmp_gt_u32_e32 vcc, s67, v50
	v_mov_b64_e32 v[12:13], v[4:5]
	v_mov_b64_e32 v[10:11], v[2:3]
	v_mov_b64_e32 v[8:9], v[0:1]
	v_mov_b64_e32 v[216:217], 0
	v_mov_b64_e32 v[218:219], 0
	s_and_saveexec_b64 s[6:7], vcc
	v_or_b32_e32 v232, s27, v50
	v_ashrrev_i32_e32 v233, 31, v232
	v_lshlrev_b64 v[232:233], 10, v[232:233]
	v_lshl_add_u64 v[232:233], v[48:49], 0, v[232:233]
	global_load_dwordx4 v[216:219], v[232:233], off
	s_or_b64 exec, exec, s[6:7]
	v_add_u32_e32 v51, 1, v50
	v_cmp_gt_u32_e32 vcc, s67, v51
	v_mov_b64_e32 v[220:221], 0
	v_mov_b64_e32 v[222:223], 0
	s_and_saveexec_b64 s[6:7], vcc
	v_or_b32_e32 v234, s27, v51
	v_ashrrev_i32_e32 v235, 31, v234
	v_lshlrev_b64 v[234:235], 10, v[234:235]
	v_lshl_add_u64 v[234:235], v[48:49], 0, v[234:235]
	global_load_dwordx4 v[220:223], v[234:235], off
	s_or_b64 exec, exec, s[6:7]
	v_add_u32_e32 v51, s28, v79
	v_cmp_gt_u32_e32 vcc, s67, v51
	v_mov_b64_e32 v[224:225], 0
	v_mov_b64_e32 v[226:227], 0
	s_and_saveexec_b64 s[6:7], vcc
	v_or_b32_e32 v236, s27, v51
	v_ashrrev_i32_e32 v237, 31, v236
	v_lshlrev_b64 v[236:237], 10, v[236:237]
	v_lshl_add_u64 v[236:237], v[48:49], 0, v[236:237]
	global_load_dwordx4 v[224:227], v[236:237], off
	s_or_b64 exec, exec, s[6:7]
	v_add_u32_e32 v50, 3, v50
	v_cmp_gt_u32_e32 vcc, s67, v50
	v_mov_b64_e32 v[228:229], 0
	v_mov_b64_e32 v[230:231], 0
	s_and_saveexec_b64 s[6:7], vcc
	v_or_b32_e32 v238, s27, v50
	v_ashrrev_i32_e32 v239, 31, v238
	v_lshlrev_b64 v[238:239], 10, v[238:239]
	v_lshl_add_u64 v[238:239], v[48:49], 0, v[238:239]
	global_load_dwordx4 v[228:231], v[238:239], off
	s_or_b64 exec, exec, s[6:7]
	s_waitcnt vmcnt(0)
	v_lshlrev_b32_e32 v52, 16, v216
	v_and_b32_e32 v53, 0xffff0000, v216
	v_lshlrev_b32_e32 v8, 16, v217
	v_and_b32_e32 v9, 0xffff0000, v217
	v_lshlrev_b32_e32 v12, 16, v218
	v_and_b32_e32 v13, 0xffff0000, v218
	v_lshlrev_b32_e32 v10, 16, v219
	v_and_b32_e32 v11, 0xffff0000, v219
	v_pk_fma_f32 v[14:15], v[22:23], v[10:11], v[6:7]
	v_pk_fma_f32 v[12:13], v[20:21], v[12:13], v[4:5]
	v_pk_fma_f32 v[10:11], v[18:19], v[8:9], v[2:3]
	v_pk_fma_f32 v[8:9], v[16:17], v[52:53], v[0:1]
	v_lshlrev_b32_e32 v56, 16, v220
	v_and_b32_e32 v57, 0xffff0000, v220
	v_lshlrev_b32_e32 v52, 16, v221
	v_and_b32_e32 v53, 0xffff0000, v221
	v_lshlrev_b32_e32 v58, 16, v222
	v_and_b32_e32 v59, 0xffff0000, v222
	v_lshlrev_b32_e32 v54, 16, v223
	v_and_b32_e32 v55, 0xffff0000, v223
	v_pk_fma_f32 v[14:15], v[30:31], v[54:55], v[14:15]
	v_pk_fma_f32 v[12:13], v[28:29], v[58:59], v[12:13]
	v_pk_fma_f32 v[10:11], v[26:27], v[52:53], v[10:11]
	v_pk_fma_f32 v[8:9], v[24:25], v[56:57], v[8:9]
	v_lshlrev_b32_e32 v56, 16, v224
	v_and_b32_e32 v57, 0xffff0000, v224
	v_lshlrev_b32_e32 v52, 16, v225
	v_and_b32_e32 v53, 0xffff0000, v225
	v_lshlrev_b32_e32 v58, 16, v226
	v_and_b32_e32 v59, 0xffff0000, v226
	v_lshlrev_b32_e32 v54, 16, v227
	v_and_b32_e32 v55, 0xffff0000, v227
	v_pk_fma_f32 v[14:15], v[38:39], v[54:55], v[14:15]
	v_pk_fma_f32 v[12:13], v[36:37], v[58:59], v[12:13]
	v_pk_fma_f32 v[10:11], v[34:35], v[52:53], v[10:11]
	v_pk_fma_f32 v[8:9], v[32:33], v[56:57], v[8:9]
	v_lshlrev_b32_e32 v54, 16, v228
	v_and_b32_e32 v55, 0xffff0000, v228
	v_lshlrev_b32_e32 v50, 16, v229
	v_and_b32_e32 v51, 0xffff0000, v229
	v_lshlrev_b32_e32 v56, 16, v230
	v_and_b32_e32 v57, 0xffff0000, v230
	v_lshlrev_b32_e32 v52, 16, v231
	v_and_b32_e32 v53, 0xffff0000, v231
	v_pk_fma_f32 v[14:15], v[46:47], v[52:53], v[14:15]
	v_pk_fma_f32 v[12:13], v[44:45], v[56:57], v[12:13]
	v_pk_fma_f32 v[10:11], v[42:43], v[50:51], v[10:11]
	v_pk_fma_f32 v[8:9], v[40:41], v[54:55], v[8:9]
	v_cvt_pk_bf16_f32 v8, v8, v9
	v_cvt_pk_bf16_f32 v9, v10, v11
	v_cvt_pk_bf16_f32 v10, v12, v13
	v_cvt_pk_bf16_f32 v11, v14, v15
	ds_write_b128 v81, v[8:11]
	v_add_u32_e32 v50, s29, v80
	v_mov_b64_e32 v[14:15], v[6:7]
	v_cmp_gt_u32_e32 vcc, s67, v50
	v_mov_b64_e32 v[12:13], v[4:5]
	v_mov_b64_e32 v[10:11], v[2:3]
	v_mov_b64_e32 v[8:9], v[0:1]
	v_mov_b64_e32 v[216:217], 0
	v_mov_b64_e32 v[218:219], 0
	s_and_saveexec_b64 s[6:7], vcc
	v_or_b32_e32 v232, s27, v50
	v_ashrrev_i32_e32 v233, 31, v232
	v_lshlrev_b64 v[232:233], 10, v[232:233]
	v_lshl_add_u64 v[232:233], v[48:49], 0, v[232:233]
	global_load_dwordx4 v[216:219], v[232:233], off
	s_or_b64 exec, exec, s[6:7]
	v_add_u32_e32 v51, 1, v50
	v_cmp_gt_u32_e32 vcc, s67, v51
	v_mov_b64_e32 v[220:221], 0
	v_mov_b64_e32 v[222:223], 0
	s_and_saveexec_b64 s[6:7], vcc
	v_or_b32_e32 v234, s27, v51
	v_ashrrev_i32_e32 v235, 31, v234
	v_lshlrev_b64 v[234:235], 10, v[234:235]
	v_lshl_add_u64 v[234:235], v[48:49], 0, v[234:235]
	global_load_dwordx4 v[220:223], v[234:235], off
	s_or_b64 exec, exec, s[6:7]
	v_add_u32_e32 v51, s28, v80
	v_cmp_gt_u32_e32 vcc, s67, v51
	v_mov_b64_e32 v[224:225], 0
	v_mov_b64_e32 v[226:227], 0
	s_and_saveexec_b64 s[6:7], vcc
	v_or_b32_e32 v236, s27, v51
	v_ashrrev_i32_e32 v237, 31, v236
	v_lshlrev_b64 v[236:237], 10, v[236:237]
	v_lshl_add_u64 v[236:237], v[48:49], 0, v[236:237]
	global_load_dwordx4 v[224:227], v[236:237], off
	s_or_b64 exec, exec, s[6:7]
	v_add_u32_e32 v50, 3, v50
	v_cmp_gt_u32_e32 vcc, s67, v50
	v_mov_b64_e32 v[228:229], 0
	v_mov_b64_e32 v[230:231], 0
	s_and_saveexec_b64 s[6:7], vcc
	v_or_b32_e32 v238, s27, v50
	v_ashrrev_i32_e32 v239, 31, v238
	v_lshlrev_b64 v[238:239], 10, v[238:239]
	v_lshl_add_u64 v[238:239], v[48:49], 0, v[238:239]
	global_load_dwordx4 v[228:231], v[238:239], off
	s_or_b64 exec, exec, s[6:7]
	s_waitcnt vmcnt(0)
	v_lshlrev_b32_e32 v52, 16, v216
	v_and_b32_e32 v53, 0xffff0000, v216
	v_lshlrev_b32_e32 v8, 16, v217
	v_and_b32_e32 v9, 0xffff0000, v217
	v_lshlrev_b32_e32 v12, 16, v218
	v_and_b32_e32 v13, 0xffff0000, v218
	v_lshlrev_b32_e32 v10, 16, v219
	v_and_b32_e32 v11, 0xffff0000, v219
	v_pk_fma_f32 v[14:15], v[22:23], v[10:11], v[6:7]
	v_pk_fma_f32 v[12:13], v[20:21], v[12:13], v[4:5]
	v_pk_fma_f32 v[10:11], v[18:19], v[8:9], v[2:3]
	v_pk_fma_f32 v[8:9], v[16:17], v[52:53], v[0:1]
	v_lshlrev_b32_e32 v56, 16, v220
	v_and_b32_e32 v57, 0xffff0000, v220
	v_lshlrev_b32_e32 v52, 16, v221
	v_and_b32_e32 v53, 0xffff0000, v221
	v_lshlrev_b32_e32 v58, 16, v222
	v_and_b32_e32 v59, 0xffff0000, v222
	v_lshlrev_b32_e32 v54, 16, v223
	v_and_b32_e32 v55, 0xffff0000, v223
	v_pk_fma_f32 v[14:15], v[30:31], v[54:55], v[14:15]
	v_pk_fma_f32 v[12:13], v[28:29], v[58:59], v[12:13]
	v_pk_fma_f32 v[10:11], v[26:27], v[52:53], v[10:11]
	v_pk_fma_f32 v[8:9], v[24:25], v[56:57], v[8:9]
	v_lshlrev_b32_e32 v56, 16, v224
	v_and_b32_e32 v57, 0xffff0000, v224
	v_lshlrev_b32_e32 v52, 16, v225
	v_and_b32_e32 v53, 0xffff0000, v225
	v_lshlrev_b32_e32 v58, 16, v226
	v_and_b32_e32 v59, 0xffff0000, v226
	v_lshlrev_b32_e32 v54, 16, v227
	v_and_b32_e32 v55, 0xffff0000, v227
	v_pk_fma_f32 v[14:15], v[38:39], v[54:55], v[14:15]
	v_pk_fma_f32 v[12:13], v[36:37], v[58:59], v[12:13]
	v_pk_fma_f32 v[10:11], v[34:35], v[52:53], v[10:11]
	v_pk_fma_f32 v[8:9], v[32:33], v[56:57], v[8:9]
	v_lshlrev_b32_e32 v52, 16, v228
	v_and_b32_e32 v53, 0xffff0000, v228
	v_lshlrev_b32_e32 v48, 16, v229
	v_and_b32_e32 v49, 0xffff0000, v229
	v_lshlrev_b32_e32 v54, 16, v230
	v_and_b32_e32 v55, 0xffff0000, v230
	v_lshlrev_b32_e32 v50, 16, v231
	v_and_b32_e32 v51, 0xffff0000, v231
	v_pk_fma_f32 v[14:15], v[46:47], v[50:51], v[14:15]
	v_pk_fma_f32 v[12:13], v[44:45], v[54:55], v[12:13]
	v_pk_fma_f32 v[10:11], v[42:43], v[48:49], v[10:11]
	v_pk_fma_f32 v[8:9], v[40:41], v[52:53], v[8:9]
	v_mov_b32_e32 v83, v191
	v_cvt_pk_bf16_f32 v8, v8, v9
	v_cvt_pk_bf16_f32 v9, v10, v11
	v_cvt_pk_bf16_f32 v10, v12, v13
	v_cvt_pk_bf16_f32 v11, v14, v15
	ds_write_b128 v82, v[8:11]
	s_waitcnt lgkmcnt(0)
	s_barrier
	v_mov_b32_e32 v85, v191
	v_and_b32_e32 v87, 15, v83
	v_lshrrev_b32_e32 v96, 4, v83
	v_bfe_u32 v97, v83, 4, 2
	s_mov_b64 s[6:7], s[74:75]
	v_bfe_u32 v86, v83, 1, 3
	v_ashrrev_i32_e32 v84, 6, v83
	v_lshlrev_b32_e32 v76, 7, v87
	v_bitop3_b32 v8, v96, v86, 3 bitop3:0x6c
	v_bitop3_b32 v13, v97, v86, 4 bitop3:0x36
	v_lshl_or_b32 v12, v84, 11, v76
	v_lshlrev_b32_e32 v8, 4, v8
	v_lshlrev_b32_e32 v13, 4, v13
	s_add_u32 s6, s6, s2
	v_add3_u32 v8, s60, v8, v12
	v_add3_u32 v12, s60, v13, v12
	s_addc_u32 s7, s7, 0
	v_lshlrev_b32_e32 v144, 4, v97
	ds_read_b128 v[8:11], v8
	ds_read_b128 v[72:75], v12
	v_lshl_add_u64 v[12:13], s[6:7], 0, v[144:145]
	s_mov_b64 s[6:7], 0x3980000
	v_lshl_add_u64 v[92:93], v[12:13], 0, s[6:7]
	s_mov_b64 s[6:7], 0x39a0000
	v_mov_b32_e32 v77, v145
	v_lshl_add_u64 v[94:95], v[12:13], 0, s[6:7]
	v_lshl_add_u64 v[60:61], v[92:93], 0, v[76:77]
	v_lshl_add_u64 v[62:63], v[94:95], 0, v[76:77]
	s_mov_b64 s[98:99], 0x1000
	v_lshl_add_u64 v[180:181], v[60:61], 0, s[98:99]
	v_lshl_add_u64 v[182:183], v[62:63], 0, s[98:99]
	global_load_dwordx4 v[104:107], v[180:181], off offset:-4096
	global_load_dwordx4 v[108:111], v[182:183], off offset:-4096
	global_load_dwordx4 v[112:115], v[180:181], off offset:-4032
	global_load_dwordx4 v[116:119], v[182:183], off offset:-4032
	global_load_dwordx4 v[120:123], v[180:181], off offset:-2048
	global_load_dwordx4 v[124:127], v[182:183], off offset:-2048
	global_load_dwordx4 v[128:131], v[180:181], off offset:-1984
	global_load_dwordx4 v[132:135], v[182:183], off offset:-1984
	global_load_dwordx4 v[136:139], v[180:181], off
	global_load_dwordx4 v[140:143], v[182:183], off
	global_load_dwordx4 v[156:159], v[180:181], off offset:64
	global_load_dwordx4 v[160:163], v[182:183], off offset:64
	global_load_dwordx4 v[164:167], v[180:181], off offset:2048
	global_load_dwordx4 v[168:171], v[182:183], off offset:2048
	global_load_dwordx4 v[172:175], v[180:181], off offset:2112
	global_load_dwordx4 v[176:179], v[182:183], off offset:2112
	v_lshrrev_b32_e32 v98, 1, v83
	v_readlane_b32 s36, v254, 22
	v_readlane_b32 s40, v254, 26
	v_readlane_b32 s41, v254, 27
	s_mov_b64 s[6:7], s[40:41]
	v_readlane_b32 s44, v254, 30
	v_readlane_b32 s45, v254, 31
	s_mov_b32 s27, 0x122e6000
	s_mov_b32 s28, 0xc1000000
	v_readlane_b32 s37, v254, 23
	v_readlane_b32 s38, v254, 24
	v_readlane_b32 s39, v254, 25
	v_readlane_b32 s42, v254, 28
	v_readlane_b32 s43, v254, 29
	v_readlane_b32 s46, v254, 32
	v_readlane_b32 s47, v254, 33
	v_readlane_b32 s48, v254, 34
	v_readlane_b32 s49, v254, 35
	v_readlane_b32 s50, v254, 36
	v_readlane_b32 s51, v254, 37
	s_waitcnt vmcnt(0) lgkmcnt(0)
	v_mfma_f32_16x16x32_bf16 v[12:15], v[104:107], v[8:11], 0
	v_mfma_f32_16x16x32_bf16 v[48:51], v[108:111], v[8:11], 0
	v_mfma_f32_16x16x32_bf16 v[68:71], v[112:115], v[72:75], v[12:15]
	v_mfma_f32_16x16x32_bf16 v[64:67], v[116:119], v[72:75], v[48:51]
	s_nop 4
	v_mfma_f32_16x16x32_bf16 v[12:15], v[120:123], v[8:11], 0
	v_mfma_f32_16x16x32_bf16 v[48:51], v[124:127], v[8:11], 0
	v_mfma_f32_16x16x32_bf16 v[60:63], v[128:131], v[72:75], v[12:15]
	s_nop 5
	v_or_b32_e32 v12, 0x1000, v76
	v_mov_b32_e32 v13, v145
	v_lshl_add_u64 v[52:53], v[92:93], 0, v[12:13]
	v_mfma_f32_16x16x32_bf16 v[56:59], v[132:135], v[72:75], v[48:51]
	v_lshl_add_u64 v[88:89], v[94:95], 0, v[12:13]
	s_nop 0
	s_nop 0
	s_nop 0
	v_mfma_f32_16x16x32_bf16 v[12:15], v[136:139], v[8:11], 0
	v_mfma_f32_16x16x32_bf16 v[48:51], v[140:143], v[8:11], 0
	v_mfma_f32_16x16x32_bf16 v[52:55], v[156:159], v[72:75], v[12:15]
	s_nop 5
	v_or_b32_e32 v12, 0x1800, v76
	v_mov_b32_e32 v13, v145
	v_lshl_add_u64 v[76:77], v[92:93], 0, v[12:13]
	v_mfma_f32_16x16x32_bf16 v[48:51], v[160:163], v[72:75], v[48:51]
	v_lshl_add_u64 v[92:93], v[94:95], 0, v[12:13]
	v_mfma_f32_16x16x32_bf16 v[12:15], v[164:167], v[8:11], 0
	v_mfma_f32_16x16x32_bf16 v[8:11], v[168:171], v[8:11], 0
	s_nop 0
	v_lshlrev_b32_e32 v76, 2, v97
	v_mov_b32_e32 v77, v145
	v_mfma_f32_16x16x32_bf16 v[12:15], v[172:175], v[72:75], v[12:15]
	v_bfe_u32 v88, v96, 1, 1
	v_mfma_f32_16x16x32_bf16 v[8:11], v[176:179], v[72:75], v[8:11]
	v_lshl_or_b32 v72, v84, 4, v87
	v_lshlrev_b32_e32 v87, 7, v72
	v_and_b32_e32 v73, 8, v98
	v_lshlrev_b32_e32 v102, 8, v72
	v_or_b32_e32 v72, s8, v76
	v_add_u32_e32 v89, s60, v73
	v_ashrrev_i32_e32 v73, 31, v72
	v_lshlrev_b64 v[90:91], 2, v[72:73]
	v_lshl_add_u64 v[72:73], s[6:7], 0, v[90:91]
	flat_load_dwordx4 v[72:75], v[72:73]
	s_mov_b64 s[6:7], s[44:45]
	v_bitop3_b32 v98, v88, v98, 7 bitop3:0x78
	v_lshl_add_u64 v[90:91], s[6:7], 0, v[90:91]
	s_mov_b64 s[6:7], s[74:75]
	flat_load_dwordx4 v[90:93], v[90:91]
	s_add_u32 s6, s6, s3
	s_addc_u32 s7, s7, 0
	v_lshl_add_u64 v[94:95], s[6:7], 0, v[144:145]
	v_add_co_u32_e32 v94, vcc, s27, v94
	v_lshlrev_b32_e32 v98, 4, v98
	s_nop 0
	v_addc_co_u32_e32 v95, vcc, 0, v95, vcc
	flat_load_dwordx4 v[94:97], v[94:95]
	v_add3_u32 v98, v89, v98, v87
	ds_read_b64 v[98:99], v98
	s_waitcnt lgkmcnt(0)
	v_lshlrev_b32_e32 v100, 16, v98
	v_and_b32_e32 v101, 0xffff0000, v98
	v_lshlrev_b32_e32 v98, 16, v99
	v_and_b32_e32 v99, 0xffff0000, v99
	s_waitcnt vmcnt(0)
	v_add_f32_e32 v68, v68, v72
	v_add_f32_e32 v69, v69, v73
	v_mul_f32_e32 v68, 0xbfb8aa3b, v68
	v_mul_f32_e32 v69, 0xbfb8aa3b, v69
	v_exp_f32_e32 v68, v68
	v_exp_f32_e32 v69, v69
	v_add_f32_e32 v64, v64, v90
	v_add_f32_e32 v65, v65, v91
	v_add_f32_e32 v68, 1.0, v68
	v_add_f32_e32 v69, 1.0, v69
	v_rcp_f32_e32 v68, v68
	v_rcp_f32_e32 v69, v69
	v_add_f32_e32 v70, v70, v74
	v_add_f32_e32 v71, v71, v75
	v_mul_f32_e32 v70, 0xbfb8aa3b, v70
	v_pk_mul_f32 v[68:69], v[68:69], s[28:29] op_sel_hi:[1,0]
	v_mul_f32_e32 v71, 0xbfb8aa3b, v71
	v_pk_mul_f32 v[72:73], v[94:95], v[68:69]
	v_exp_f32_e32 v70, v70
	v_pk_add_f32 v[90:91], v[72:73], v[72:73]
	v_mul_f32_e32 v68, 0x3fb8aa3b, v72
	v_fmamk_f32 v69, v90, 0x3ab60b61, v195
	v_exp_f32_e32 v68, v68
	v_fmaak_f32 v69, v90, v69, 0x3d2aaaab
	v_fmaak_f32 v69, v90, v69, 0x3e2aaaab
	v_exp_f32_e32 v71, v71
	v_fma_f32 v69, v90, v69, 0.5
	v_fma_f32 v69, v90, v69, 1.0
	v_mul_f32_e64 v69, v69, -v90
	v_fma_f32 v72, -v68, v68, 1.0
	v_cmp_lt_f32_e64 s[6:7], s84, v90
	v_add_f32_e32 v70, 1.0, v70
	v_add_f32_e32 v71, 1.0, v71
	v_cndmask_b32_e64 v69, v72, v69, s[6:7]
	v_sqrt_f32_e32 v72, v69
	v_mul_f32_e32 v69, 0x3fb8aa3b, v73
	v_fmamk_f32 v73, v91, 0x3ab60b61, v195
	v_rcp_f32_e32 v70, v70
	v_rcp_f32_e32 v71, v71
	v_exp_f32_e32 v69, v69
	v_fmaak_f32 v73, v91, v73, 0x3d2aaaab
	v_fmaak_f32 v73, v91, v73, 0x3e2aaaab
	v_fma_f32 v73, v91, v73, 0.5
	v_fma_f32 v73, v91, v73, 1.0
	v_pk_mul_f32 v[70:71], v[70:71], s[28:29] op_sel_hi:[1,0]
	v_cmp_lt_f32_e32 vcc, s84, v91
	v_mul_f32_e64 v73, v73, -v91
	v_fma_f32 v90, -v69, v69, 1.0
	v_pk_mul_f32 v[74:75], v[96:97], v[70:71]
	v_cndmask_b32_e32 v73, v90, v73, vcc
	v_pk_add_f32 v[90:91], v[74:75], v[74:75]
	v_mul_f32_e32 v70, 0x3fb8aa3b, v74
	v_fmamk_f32 v71, v90, 0x3ab60b61, v195
	v_exp_f32_e32 v70, v70
	v_fmaak_f32 v71, v90, v71, 0x3d2aaaab
	v_fmaak_f32 v71, v90, v71, 0x3e2aaaab
	v_fma_f32 v71, v90, v71, 0.5
	v_fma_f32 v71, v90, v71, 1.0
	v_mul_f32_e64 v71, v71, -v90
	v_fma_f32 v74, -v70, v70, 1.0
	v_cmp_lt_f32_e64 s[6:7], s84, v90
	v_add_f32_e32 v66, v66, v92
	v_add_f32_e32 v67, v67, v93
	v_cndmask_b32_e64 v71, v74, v71, s[6:7]
	v_sqrt_f32_e32 v74, v71
	v_mul_f32_e32 v71, 0x3fb8aa3b, v75
	v_fmamk_f32 v75, v91, 0x3ab60b61, v195
	v_mul_f32_e32 v64, 0xbfb8aa3b, v64
	v_mul_f32_e32 v65, 0xbfb8aa3b, v65
	v_mul_f32_e32 v66, 0xbfb8aa3b, v66
	v_mul_f32_e32 v67, 0xbfb8aa3b, v67
	v_exp_f32_e32 v71, v71
	v_fmaak_f32 v75, v91, v75, 0x3d2aaaab
	v_exp_f32_e32 v64, v64
	v_exp_f32_e32 v65, v65
	v_exp_f32_e32 v66, v66
	v_exp_f32_e32 v67, v67
	v_fmaak_f32 v75, v91, v75, 0x3e2aaaab
	v_fma_f32 v75, v91, v75, 0.5
	v_fma_f32 v75, v91, v75, 1.0
	v_cmp_lt_f32_e32 vcc, s84, v91
	v_mul_f32_e64 v75, v75, -v91
	v_fma_f32 v90, -v71, v71, 1.0
	v_add_f32_e32 v64, 1.0, v64
	v_add_f32_e32 v65, 1.0, v65
	v_add_f32_e32 v66, 1.0, v66
	v_add_f32_e32 v67, 1.0, v67
	v_cndmask_b32_e32 v75, v90, v75, vcc
	v_rcp_f32_e32 v64, v64
	v_rcp_f32_e32 v65, v65
	v_sqrt_f32_e32 v73, v73
	v_rcp_f32_e32 v66, v66
	v_rcp_f32_e32 v67, v67
	v_sqrt_f32_e32 v75, v75
	v_pk_mul_f32 v[64:65], v[64:65], v[72:73]
	s_mov_b64 s[6:7], s[40:41]
	v_pk_mul_f32 v[72:73], v[64:65], v[100:101]
	v_pk_mul_f32 v[66:67], v[66:67], v[74:75]
	v_lshl_add_u64 v[64:65], v[76:77], 0, s[8:9]
	v_pk_mul_f32 v[74:75], v[66:67], v[98:99]
	v_add3_u32 v66, s60, v102, v144
	ds_write_b128 v66, v[68:71] offset:8192
	ds_write_b128 v66, v[72:75] offset:24576
	v_lshlrev_b64 v[64:65], 2, v[64:65]
	v_lshl_add_u64 v[68:69], s[6:7], 0, v[64:65]
	s_mov_b64 s[6:7], s[44:45]
	flat_load_dwordx4 v[68:71], v[68:69] offset:64
	v_bitop3_b32 v67, v88, v86, 2 bitop3:0x36
	v_lshl_add_u64 v[72:73], s[6:7], 0, v[64:65]
	flat_load_dwordx4 v[72:75], v[72:73] offset:64
	s_mov_b64 s[6:7], s[74:75]
	s_add_u32 s6, s6, s3
	s_addc_u32 s7, s7, 0
	v_lshl_add_u64 v[76:77], s[6:7], 0, v[144:145]
	v_add_co_u32_e32 v76, vcc, s27, v76
	v_lshlrev_b32_e32 v67, 4, v67
	s_nop 0
	v_addc_co_u32_e32 v77, vcc, 0, v77, vcc
	flat_load_dwordx4 v[90:93], v[76:77] offset:64
	v_add3_u32 v67, v89, v67, v87
	ds_read_b64 v[76:77], v67
	s_waitcnt lgkmcnt(0)
	v_lshlrev_b32_e32 v94, 16, v76
	v_and_b32_e32 v95, 0xffff0000, v76
	v_lshlrev_b32_e32 v76, 16, v77
	v_and_b32_e32 v77, 0xffff0000, v77
	s_waitcnt vmcnt(0)
	v_add_f32_e32 v60, v60, v68
	v_mul_f32_e32 v60, 0xbfb8aa3b, v60
	v_exp_f32_e32 v60, v60
	v_add_f32_e32 v62, v62, v70
	v_add_f32_e32 v56, v56, v72
	v_mul_f32_e32 v56, 0xbfb8aa3b, v56
	v_exp_f32_e32 v56, v56
	v_add_f32_e32 v58, v58, v74
	v_mul_f32_e32 v58, 0xbfb8aa3b, v58
	v_exp_f32_e32 v58, v58
	v_add_f32_e32 v56, 1.0, v56
	v_rcp_f32_e32 v68, v56
	v_add_f32_e32 v56, v61, v69
	v_mul_f32_e32 v56, 0xbfb8aa3b, v56
	v_exp_f32_e32 v56, v56
	v_add_f32_e32 v60, 1.0, v60
	v_rcp_f32_e32 v60, v60
	v_add_f32_e32 v58, 1.0, v58
	v_add_f32_e32 v56, 1.0, v56
	v_rcp_f32_e32 v61, v56
	v_add_f32_e32 v56, v57, v73
	v_mul_f32_e32 v56, 0xbfb8aa3b, v56
	v_exp_f32_e32 v56, v56
	v_rcp_f32_e32 v70, v58
	v_add_f32_e32 v58, v63, v71
	v_mul_f32_e32 v58, 0xbfb8aa3b, v58
	v_add_f32_e32 v56, 1.0, v56
	v_rcp_f32_e32 v69, v56
	v_pk_mul_f32 v[56:57], v[60:61], s[28:29] op_sel_hi:[1,0]
	v_exp_f32_e32 v58, v58
	v_pk_mul_f32 v[60:61], v[90:91], v[56:57]
	v_mul_f32_e32 v62, 0xbfb8aa3b, v62
	v_pk_add_f32 v[72:73], v[60:61], v[60:61]
	v_mul_f32_e32 v56, 0x3fb8aa3b, v60
	v_fmamk_f32 v57, v72, 0x3ab60b61, v195
	v_exp_f32_e32 v56, v56
	v_fmaak_f32 v57, v72, v57, 0x3d2aaaab
	v_exp_f32_e32 v62, v62
	v_fmaak_f32 v57, v72, v57, 0x3e2aaaab
	v_add_f32_e32 v58, 1.0, v58
	v_fma_f32 v57, v72, v57, 0.5
	v_rcp_f32_e32 v63, v58
	v_add_f32_e32 v58, v59, v75
	v_fma_f32 v57, v72, v57, 1.0
	v_mul_f32_e32 v58, 0xbfb8aa3b, v58
	v_mul_f32_e64 v57, v57, -v72
	v_fma_f32 v60, -v56, v56, 1.0
	v_cmp_lt_f32_e64 s[6:7], s84, v72
	v_add_f32_e32 v62, 1.0, v62
	v_exp_f32_e32 v58, v58
	v_cndmask_b32_e64 v57, v60, v57, s[6:7]
	v_rcp_f32_e32 v62, v62
	v_sqrt_f32_e32 v60, v57
	v_mul_f32_e32 v57, 0x3fb8aa3b, v61
	v_fmamk_f32 v61, v73, 0x3ab60b61, v195
	v_fmaak_f32 v61, v73, v61, 0x3d2aaaab
	v_fmaak_f32 v61, v73, v61, 0x3e2aaaab
	v_add_f32_e32 v58, 1.0, v58
	v_fma_f32 v61, v73, v61, 0.5
	v_rcp_f32_e32 v71, v58
	v_pk_mul_f32 v[58:59], v[62:63], s[28:29] op_sel_hi:[1,0]
	v_fma_f32 v61, v73, v61, 1.0
	v_pk_mul_f32 v[62:63], v[92:93], v[58:59]
	v_cmp_lt_f32_e32 vcc, s84, v73
	v_mul_f32_e64 v61, v61, -v73
	v_pk_add_f32 v[72:73], v[62:63], v[62:63]
	v_mul_f32_e32 v58, 0x3fb8aa3b, v62
	v_fmamk_f32 v59, v72, 0x3ab60b61, v195
	v_exp_f32_e32 v58, v58
	v_fmaak_f32 v59, v72, v59, 0x3d2aaaab
	v_fmaak_f32 v59, v72, v59, 0x3e2aaaab
	v_fma_f32 v59, v72, v59, 0.5
	v_fma_f32 v59, v72, v59, 1.0
	v_mul_f32_e64 v59, v59, -v72
	v_fma_f32 v62, -v58, v58, 1.0
	v_cmp_lt_f32_e64 s[6:7], s84, v72
	v_exp_f32_e32 v57, v57
	s_nop 0
	v_cndmask_b32_e64 v59, v62, v59, s[6:7]
	v_sqrt_f32_e32 v62, v59
	v_mul_f32_e32 v59, 0x3fb8aa3b, v63
	v_fmamk_f32 v63, v73, 0x3ab60b61, v195
	v_exp_f32_e32 v59, v59
	v_fmaak_f32 v63, v73, v63, 0x3d2aaaab
	v_fmaak_f32 v63, v73, v63, 0x3e2aaaab
	v_fma_f32 v63, v73, v63, 0.5
	v_fma_f32 v67, -v57, v57, 1.0
	v_fma_f32 v63, v73, v63, 1.0
	v_cndmask_b32_e32 v61, v67, v61, vcc
	v_cmp_lt_f32_e32 vcc, s84, v73
	v_mul_f32_e64 v63, v63, -v73
	v_fma_f32 v67, -v59, v59, 1.0
	v_cndmask_b32_e32 v63, v67, v63, vcc
	v_sqrt_f32_e32 v61, v61
	v_sqrt_f32_e32 v63, v63
	s_mov_b64 s[6:7], s[40:41]
	v_bitop3_b32 v67, v88, v86, 4 bitop3:0x36
	v_pk_mul_f32 v[60:61], v[68:69], v[60:61]
	v_pk_mul_f32 v[62:63], v[70:71], v[62:63]
	v_pk_mul_f32 v[60:61], v[60:61], v[94:95]
	v_pk_mul_f32 v[62:63], v[62:63], v[76:77]
	ds_write_b128 v66, v[56:59] offset:8256
	ds_write_b128 v66, v[60:63] offset:24640
	v_lshlrev_b32_e32 v67, 4, v67
	v_lshl_add_u64 v[56:57], s[6:7], 0, v[64:65]
	s_mov_b64 s[6:7], s[44:45]
	flat_load_dwordx4 v[56:59], v[56:57] offset:128
	v_add3_u32 v67, v89, v67, v87
	v_lshl_add_u64 v[60:61], s[6:7], 0, v[64:65]
	flat_load_dwordx4 v[60:63], v[60:61] offset:128
	s_mov_b64 s[6:7], s[74:75]
	s_add_u32 s6, s6, s3
	s_addc_u32 s7, s7, 0
	v_lshl_add_u64 v[68:69], s[6:7], 0, v[144:145]
	v_add_co_u32_e32 v68, vcc, s27, v68
	ds_read_b64 v[72:73], v67
	s_nop 0
	v_addc_co_u32_e32 v69, vcc, 0, v69, vcc
	flat_load_dwordx4 v[68:71], v[68:69] offset:128
	s_waitcnt lgkmcnt(0)
	v_lshlrev_b32_e32 v74, 16, v72
	v_and_b32_e32 v75, 0xffff0000, v72
	v_lshlrev_b32_e32 v72, 16, v73
	v_and_b32_e32 v73, 0xffff0000, v73
	s_waitcnt vmcnt(0)
	v_add_f32_e32 v52, v52, v56
	v_mul_f32_e32 v52, 0xbfb8aa3b, v52
	v_exp_f32_e32 v52, v52
	v_add_f32_e32 v54, v54, v58
	v_add_f32_e32 v48, v48, v60
	v_mul_f32_e32 v48, 0xbfb8aa3b, v48
	v_exp_f32_e32 v48, v48
	v_add_f32_e32 v50, v50, v62
	v_mul_f32_e32 v50, 0xbfb8aa3b, v50
	v_add_f32_e32 v52, 1.0, v52
	v_add_f32_e32 v48, 1.0, v48
	v_rcp_f32_e32 v56, v48
	v_add_f32_e32 v48, v53, v57
	v_mul_f32_e32 v48, 0xbfb8aa3b, v48
	v_exp_f32_e32 v48, v48
	v_exp_f32_e32 v50, v50
	v_rcp_f32_e32 v52, v52
	v_mul_f32_e32 v54, 0xbfb8aa3b, v54
	v_add_f32_e32 v48, 1.0, v48
	v_rcp_f32_e32 v53, v48
	v_add_f32_e32 v48, v49, v61
	v_mul_f32_e32 v48, 0xbfb8aa3b, v48
	v_exp_f32_e32 v48, v48
	v_add_f32_e32 v50, 1.0, v50
	v_rcp_f32_e32 v58, v50
	v_add_f32_e32 v50, v55, v59
	v_add_f32_e32 v48, 1.0, v48
	v_rcp_f32_e32 v57, v48
	v_pk_mul_f32 v[48:49], v[52:53], s[28:29] op_sel_hi:[1,0]
	v_mul_f32_e32 v50, 0xbfb8aa3b, v50
	v_pk_mul_f32 v[52:53], v[68:69], v[48:49]
	v_exp_f32_e32 v50, v50
	v_pk_add_f32 v[60:61], v[52:53], v[52:53]
	v_mul_f32_e32 v48, 0x3fb8aa3b, v52
	v_fmamk_f32 v49, v60, 0x3ab60b61, v195
	v_exp_f32_e32 v48, v48
	v_fmaak_f32 v49, v60, v49, 0x3d2aaaab
	v_fmaak_f32 v49, v60, v49, 0x3e2aaaab
	v_exp_f32_e32 v54, v54
	v_fma_f32 v49, v60, v49, 0.5
	v_add_f32_e32 v50, 1.0, v50
	v_fma_f32 v49, v60, v49, 1.0
	v_rcp_f32_e32 v55, v50
	v_add_f32_e32 v50, v51, v63
	v_mul_f32_e64 v49, v49, -v60
	v_fma_f32 v52, -v48, v48, 1.0
	v_cmp_lt_f32_e64 s[6:7], s84, v60
	v_mul_f32_e32 v50, 0xbfb8aa3b, v50
	v_add_f32_e32 v54, 1.0, v54
	v_cndmask_b32_e64 v49, v52, v49, s[6:7]
	v_exp_f32_e32 v50, v50
	v_sqrt_f32_e32 v52, v49
	v_mul_f32_e32 v49, 0x3fb8aa3b, v53
	v_fmamk_f32 v53, v61, 0x3ab60b61, v195
	v_rcp_f32_e32 v54, v54
	v_exp_f32_e32 v49, v49
	v_fmaak_f32 v53, v61, v53, 0x3d2aaaab
	v_fmaak_f32 v53, v61, v53, 0x3e2aaaab
	v_fma_f32 v53, v61, v53, 0.5
	v_add_f32_e32 v50, 1.0, v50
	v_fma_f32 v53, v61, v53, 1.0
	v_rcp_f32_e32 v59, v50
	v_pk_mul_f32 v[50:51], v[54:55], s[28:29] op_sel_hi:[1,0]
	v_cmp_lt_f32_e32 vcc, s84, v61
	v_mul_f32_e64 v53, v53, -v61
	v_fma_f32 v60, -v49, v49, 1.0
	v_pk_mul_f32 v[54:55], v[70:71], v[50:51]
	v_cndmask_b32_e32 v53, v60, v53, vcc
	v_pk_add_f32 v[60:61], v[54:55], v[54:55]
	v_mul_f32_e32 v50, 0x3fb8aa3b, v54
	v_fmamk_f32 v51, v60, 0x3ab60b61, v195
	v_exp_f32_e32 v50, v50
	v_fmaak_f32 v51, v60, v51, 0x3d2aaaab
	v_fmaak_f32 v51, v60, v51, 0x3e2aaaab
	v_fma_f32 v51, v60, v51, 0.5
	v_fma_f32 v51, v60, v51, 1.0
	v_mul_f32_e64 v51, v51, -v60
	v_fma_f32 v54, -v50, v50, 1.0
	v_cmp_lt_f32_e64 s[6:7], s84, v60
	v_cmp_lt_f32_e32 vcc, s84, v61
	v_sqrt_f32_e32 v53, v53
	v_cndmask_b32_e64 v51, v54, v51, s[6:7]
	v_sqrt_f32_e32 v54, v51
	v_mul_f32_e32 v51, 0x3fb8aa3b, v55
	v_fmamk_f32 v55, v61, 0x3ab60b61, v195
	v_exp_f32_e32 v51, v51
	v_fmaak_f32 v55, v61, v55, 0x3d2aaaab
	v_fmaak_f32 v55, v61, v55, 0x3e2aaaab
	v_fma_f32 v55, v61, v55, 0.5
	v_fma_f32 v55, v61, v55, 1.0
	v_mul_f32_e64 v55, v55, -v61
	v_fma_f32 v60, -v51, v51, 1.0
	v_cndmask_b32_e32 v55, v60, v55, vcc
	v_sqrt_f32_e32 v55, v55
	v_pk_mul_f32 v[52:53], v[56:57], v[52:53]
	s_mov_b64 s[6:7], s[40:41]
	v_pk_mul_f32 v[52:53], v[52:53], v[74:75]
	v_pk_mul_f32 v[54:55], v[58:59], v[54:55]
	v_bitop3_b32 v60, v88, v86, 6 bitop3:0x36
	v_pk_mul_f32 v[54:55], v[54:55], v[72:73]
	ds_write_b128 v66, v[48:51] offset:8320
	ds_write_b128 v66, v[52:55] offset:24704
	v_lshlrev_b32_e32 v60, 4, v60
	v_lshl_add_u64 v[48:49], s[6:7], 0, v[64:65]
	s_mov_b64 s[6:7], s[44:45]
	flat_load_dwordx4 v[48:51], v[48:49] offset:192
	v_add3_u32 v60, v89, v60, v87
	v_lshl_add_u64 v[52:53], s[6:7], 0, v[64:65]
	flat_load_dwordx4 v[52:55], v[52:53] offset:192
	s_mov_b64 s[6:7], s[74:75]
	s_add_u32 s6, s6, s3
	s_addc_u32 s7, s7, 0
	v_lshl_add_u64 v[56:57], s[6:7], 0, v[144:145]
	v_add_co_u32_e32 v56, vcc, s27, v56
	ds_read_b64 v[60:61], v60
	s_nop 0
	v_addc_co_u32_e32 v57, vcc, 0, v57, vcc
	flat_load_dwordx4 v[56:59], v[56:57] offset:192
	s_waitcnt lgkmcnt(0)
	v_lshlrev_b32_e32 v62, 16, v60
	v_and_b32_e32 v63, 0xffff0000, v60
	v_lshlrev_b32_e32 v60, 16, v61
	v_and_b32_e32 v61, 0xffff0000, v61
	s_waitcnt vmcnt(0)
	v_add_f32_e32 v12, v12, v48
	v_mul_f32_e32 v12, 0xbfb8aa3b, v12
	v_exp_f32_e32 v12, v12
	v_add_f32_e32 v14, v14, v50
	v_add_f32_e32 v8, v8, v52
	v_mul_f32_e32 v8, 0xbfb8aa3b, v8
	v_exp_f32_e32 v8, v8
	v_add_f32_e32 v10, v10, v54
	v_mul_f32_e32 v10, 0xbfb8aa3b, v10
	v_add_f32_e32 v12, 1.0, v12
	v_add_f32_e32 v8, 1.0, v8
	v_rcp_f32_e32 v48, v8
	v_add_f32_e32 v8, v13, v49
	v_mul_f32_e32 v8, 0xbfb8aa3b, v8
	v_exp_f32_e32 v8, v8
	v_exp_f32_e32 v10, v10
	v_rcp_f32_e32 v12, v12
	v_mul_f32_e32 v14, 0xbfb8aa3b, v14
	v_add_f32_e32 v8, 1.0, v8
	v_rcp_f32_e32 v13, v8
	v_add_f32_e32 v8, v9, v53
	v_mul_f32_e32 v8, 0xbfb8aa3b, v8
	v_exp_f32_e32 v8, v8
	v_add_f32_e32 v10, 1.0, v10
	v_rcp_f32_e32 v50, v10
	v_add_f32_e32 v10, v15, v51
	v_add_f32_e32 v8, 1.0, v8
	v_rcp_f32_e32 v49, v8
	v_pk_mul_f32 v[8:9], v[12:13], s[28:29] op_sel_hi:[1,0]
	v_mul_f32_e32 v10, 0xbfb8aa3b, v10
	v_pk_mul_f32 v[12:13], v[56:57], v[8:9]
	v_exp_f32_e32 v10, v10
	v_pk_add_f32 v[52:53], v[12:13], v[12:13]
	v_mul_f32_e32 v8, 0x3fb8aa3b, v12
	v_fmamk_f32 v9, v52, 0x3ab60b61, v195
	v_exp_f32_e32 v8, v8
	v_fmaak_f32 v9, v52, v9, 0x3d2aaaab
	v_fmaak_f32 v9, v52, v9, 0x3e2aaaab
	v_exp_f32_e32 v14, v14
	v_fma_f32 v9, v52, v9, 0.5
	v_add_f32_e32 v10, 1.0, v10
	v_fma_f32 v9, v52, v9, 1.0
	v_rcp_f32_e32 v15, v10
	v_add_f32_e32 v10, v11, v55
	v_mul_f32_e64 v9, v9, -v52
	v_fma_f32 v12, -v8, v8, 1.0
	v_cmp_lt_f32_e64 s[6:7], s84, v52
	v_mul_f32_e32 v10, 0xbfb8aa3b, v10
	v_add_f32_e32 v14, 1.0, v14
	v_cndmask_b32_e64 v9, v12, v9, s[6:7]
	v_exp_f32_e32 v10, v10
	v_sqrt_f32_e32 v12, v9
	v_mul_f32_e32 v9, 0x3fb8aa3b, v13
	v_fmamk_f32 v13, v53, 0x3ab60b61, v195
	v_rcp_f32_e32 v14, v14
	v_exp_f32_e32 v9, v9
	v_fmaak_f32 v13, v53, v13, 0x3d2aaaab
	v_fmaak_f32 v13, v53, v13, 0x3e2aaaab
	v_fma_f32 v13, v53, v13, 0.5
	v_add_f32_e32 v10, 1.0, v10
	v_fma_f32 v13, v53, v13, 1.0
	v_rcp_f32_e32 v51, v10
	v_pk_mul_f32 v[10:11], v[14:15], s[28:29] op_sel_hi:[1,0]
	v_cmp_lt_f32_e32 vcc, s84, v53
	v_mul_f32_e64 v13, v13, -v53
	v_fma_f32 v52, -v9, v9, 1.0
	v_pk_mul_f32 v[14:15], v[58:59], v[10:11]
	v_cndmask_b32_e32 v13, v52, v13, vcc
	v_pk_add_f32 v[52:53], v[14:15], v[14:15]
	v_mul_f32_e32 v10, 0x3fb8aa3b, v14
	v_fmamk_f32 v11, v52, 0x3ab60b61, v195
	v_exp_f32_e32 v10, v10
	v_fmaak_f32 v11, v52, v11, 0x3d2aaaab
	v_fmaak_f32 v11, v52, v11, 0x3e2aaaab
	v_fma_f32 v11, v52, v11, 0.5
	v_fma_f32 v11, v52, v11, 1.0
	v_mul_f32_e64 v11, v11, -v52
	v_fma_f32 v14, -v10, v10, 1.0
	v_cmp_lt_f32_e64 s[6:7], s84, v52
	v_cmp_lt_f32_e32 vcc, s84, v53
	v_sqrt_f32_e32 v13, v13
	v_cndmask_b32_e64 v11, v14, v11, s[6:7]
	v_sqrt_f32_e32 v14, v11
	v_mul_f32_e32 v11, 0x3fb8aa3b, v15
	v_fmamk_f32 v15, v53, 0x3ab60b61, v195
	v_exp_f32_e32 v11, v11
	v_fmaak_f32 v15, v53, v15, 0x3d2aaaab
	v_fmaak_f32 v15, v53, v15, 0x3e2aaaab
	v_fma_f32 v15, v53, v15, 0.5
	v_fma_f32 v15, v53, v15, 1.0
	v_mul_f32_e64 v15, v15, -v53
	v_fma_f32 v52, -v11, v11, 1.0
	v_cndmask_b32_e32 v15, v52, v15, vcc
	v_sqrt_f32_e32 v15, v15
	v_pk_mul_f32 v[12:13], v[48:49], v[12:13]
	v_cmp_gt_u32_e32 vcc, 64, v83
	v_pk_mul_f32 v[12:13], v[12:13], v[62:63]
	v_pk_mul_f32 v[14:15], v[50:51], v[14:15]
	s_nop 0
	v_pk_mul_f32 v[14:15], v[14:15], v[60:61]
	ds_write_b128 v66, v[8:11] offset:8384
	ds_write_b128 v66, v[12:15] offset:24768
	v_and_b32_e32 v8, 63, v85
	v_lshlrev_b32_e32 v9, 2, v8
	v_lshl_or_b32 v9, v84, 12, v9
	v_add_u32_e32 v9, s60, v9
	s_waitcnt lgkmcnt(0)
	s_barrier
	ds_read2st64_b32 v[10:11], v9 offset0:32 offset1:33
	ds_read2st64_b32 v[12:13], v9 offset0:96 offset1:97
	ds_read2st64_b32 v[14:15], v9 offset0:34 offset1:35
	ds_read2st64_b32 v[48:49], v9 offset0:98 offset1:99
	s_waitcnt lgkmcnt(2)
	v_fma_f32 v12, 0, v10, v12
	v_fmac_f32_e32 v13, v12, v11
	v_mul_f32_e32 v10, v10, v11
	s_waitcnt lgkmcnt(0)
	v_fma_f32 v11, v13, v14, v48
	ds_read2st64_b32 v[12:13], v9 offset0:36 offset1:37
	ds_read2st64_b32 v[50:51], v9 offset0:100 offset1:101
	v_fmac_f32_e32 v49, v11, v15
	v_mov_b32_e32 v58, v14
	v_mul_f32_e32 v14, v10, v14
	v_mul_f32_e32 v14, v14, v15
	s_waitcnt lgkmcnt(0)
	v_fma_f32 v11, v49, v12, v50
	ds_read2st64_b32 v[48:49], v9 offset0:38 offset1:39
	ds_read2st64_b32 v[52:53], v9 offset0:102 offset1:103
	v_fmac_f32_e32 v51, v11, v13
	s_waitcnt lgkmcnt(1)
	v_mov_b32_e32 v62, v48
	s_waitcnt lgkmcnt(0)
	v_fma_f32 v11, v51, v48, v52
	ds_read2st64_b32 v[50:51], v9 offset0:40 offset1:41
	ds_read2st64_b32 v[54:55], v9 offset0:104 offset1:105
	v_fmac_f32_e32 v53, v11, v49
	s_waitcnt lgkmcnt(1)
	v_mov_b32_e32 v59, v51
	s_waitcnt lgkmcnt(0)
	v_fmac_f32_e32 v54, v53, v50
	ds_read2st64_b32 v[52:53], v9 offset0:42 offset1:43
	ds_read2st64_b32 v[56:57], v9 offset0:106 offset1:107
	v_mov_b32_e32 v11, v54
	v_mov_b32_e32 v54, v15
	v_pk_fma_f32 v[10:11], v[10:11], v[58:59], v[54:55]
	v_mov_b32_e32 v58, v13
	v_mov_b32_e32 v15, v11
	v_mov_b32_e32 v10, v12
	s_waitcnt lgkmcnt(1)
	v_mov_b32_e32 v11, v52
	v_pk_mul_f32 v[54:55], v[14:15], v[10:11]
	v_mov_b32_e32 v12, v13
	s_waitcnt lgkmcnt(0)
	v_mov_b32_e32 v59, v56
	v_pk_mul_f32 v[12:13], v[54:55], v[12:13]
	v_pk_fma_f32 v[10:11], v[14:15], v[10:11], v[58:59]
	ds_read2st64_b32 v[14:15], v9 offset0:44 offset1:45
	ds_read2st64_b32 v[54:55], v9 offset0:108 offset1:109
	ds_read2st64_b32 v[58:59], v9 offset0:46 offset1:47
	ds_read2st64_b32 v[60:61], v9 offset0:110 offset1:111
	v_and_b32_e32 v56, 0x1fffffc0, v83
	v_lshl_add_u32 v9, v8, 3, s60
	v_mov_b32_e32 v10, v12
	v_lshl_add_u32 v64, v56, 3, v9
	v_mov_b32_e32 v63, v53
	v_pk_mul_f32 v[12:13], v[12:13], v[48:49]
	v_mov_b32_e32 v48, v49
	v_mov_b32_e32 v56, v49
	v_pk_mul_f32 v[12:13], v[12:13], v[48:49]
	v_pk_fma_f32 v[10:11], v[10:11], v[62:63], v[56:57]
	v_mov_b32_e32 v56, v51
	v_mov_b32_e32 v13, v11
	v_mov_b32_e32 v10, v50
	s_waitcnt lgkmcnt(3)
	v_mov_b32_e32 v11, v14
	v_pk_mul_f32 v[48:49], v[12:13], v[10:11]
	v_mov_b32_e32 v50, v51
	s_waitcnt lgkmcnt(2)
	v_mov_b32_e32 v57, v54
	v_pk_mul_f32 v[48:49], v[48:49], v[50:51]
	v_pk_fma_f32 v[10:11], v[12:13], v[10:11], v[56:57]
	v_mov_b32_e32 v12, v52
	v_mov_b32_e32 v10, v48
	v_mov_b32_e32 v13, v15
	v_pk_mul_f32 v[48:49], v[48:49], v[52:53]
	v_mov_b32_e32 v50, v53
	v_mov_b32_e32 v54, v53
	v_pk_mul_f32 v[48:49], v[48:49], v[50:51]
	v_pk_fma_f32 v[10:11], v[10:11], v[12:13], v[54:55]
	v_mov_b32_e32 v50, v15
	v_mov_b32_e32 v49, v11
	v_mov_b32_e32 v10, v14
	s_waitcnt lgkmcnt(1)
	v_mov_b32_e32 v11, v58
	v_pk_mul_f32 v[12:13], v[48:49], v[10:11]
	v_mov_b32_e32 v14, v15
	s_waitcnt lgkmcnt(0)
	v_mov_b32_e32 v51, v60
	v_pk_mul_f32 v[12:13], v[12:13], v[14:15]
	v_pk_fma_f32 v[10:11], v[48:49], v[10:11], v[50:51]
	v_mov_b32_e32 v14, v59
	v_mov_b32_e32 v10, v12
	v_pk_mul_f32 v[12:13], v[12:13], v[58:59]
	v_mov_b32_e32 v60, v59
	v_pk_mul_f32 v[12:13], v[12:13], v[14:15]
	v_pk_fma_f32 v[10:11], v[10:11], v[58:59], v[60:61]
	s_nop 0
	v_mov_b32_e32 v13, v11
	ds_write_b64 v64, v[12:13] offset:40960
	s_waitcnt lgkmcnt(0)
	s_barrier
	s_and_saveexec_b64 s[6:7], vcc
	s_xor_b64 s[6:7], exec, s[6:7]
	s_cbranch_execz .LBB0_401
	s_lshl_b32 s27, s26, 7
	ds_read2st64_b64 v[10:13], v9 offset0:80 offset1:81
	ds_read2st64_b64 v[48:51], v9 offset0:82 offset1:83
	s_or_b32 s28, s27, s25
	s_ashr_i32 s29, s28, 31
	s_lshl_b64 s[28:29], s[28:29], 12
	s_mov_b64 s[30:31], s[74:75]
	s_add_u32 s27, s30, s28
	s_waitcnt lgkmcnt(1)
	v_fma_f32 v9, 0, v10, v11
	s_addc_u32 s29, s31, s29
	s_lshl_b32 s28, s23, 3
	v_fmac_f32_e32 v13, v9, v12
	s_add_u32 s28, s27, s28
	v_mul_f32_e32 v10, v10, v12
	s_waitcnt lgkmcnt(0)
	v_fma_f32 v11, v13, v48, v49
	v_mov_b32_e32 v49, v50
	s_addc_u32 s29, s29, 0
	v_lshlrev_b32_e32 v144, 3, v8
	v_pk_mul_f32 v[12:13], v[10:11], v[48:49]
	v_lshl_add_u64 v[8:9], s[28:29], 0, v[144:145]
	v_pk_mul_f32 v[12:13], v[12:13], v[50:51]
	v_pk_fma_f32 v[10:11], v[10:11], v[48:49], v[50:51]
	v_add_co_u32_e32 v8, vcc, 0x115e0000, v8
	v_mov_b32_e32 v13, v11
	s_nop 0
	v_addc_co_u32_e32 v9, vcc, 0, v9, vcc
	flat_store_dwordx2 v[8:9], v[12:13]
.LBB0_401:
	s_or_b64 exec, exec, s[6:7]
	v_mov_b32_e32 v75, v191
	s_waitcnt lgkmcnt(0)
	s_barrier
	v_mov_b32_e32 v74, v191
	v_and_b32_e32 v83, 15, v75
	v_lshrrev_b32_e32 v96, 4, v75
	v_bfe_u32 v97, v75, 4, 2
	s_mov_b64 s[6:7], s[74:75]
	v_bfe_u32 v77, v75, 1, 3
	v_ashrrev_i32_e32 v76, 6, v75
	v_lshlrev_b32_e32 v72, 7, v83
	v_bitop3_b32 v8, v96, v77, 3 bitop3:0x6c
	v_bitop3_b32 v13, v97, v77, 4 bitop3:0x36
	v_lshl_or_b32 v12, v76, 11, v72
	v_lshlrev_b32_e32 v8, 4, v8
	v_lshlrev_b32_e32 v13, 4, v13
	s_add_u32 s6, s6, s24
	v_add3_u32 v8, s60, v8, v12
	v_add3_u32 v12, s60, v13, v12
	s_addc_u32 s7, s7, 0
	v_lshlrev_b32_e32 v144, 4, v97
	ds_read_b128 v[8:11], v8
	ds_read_b128 v[84:87], v12
	v_lshl_add_u64 v[12:13], s[6:7], 0, v[144:145]
	s_mov_b64 s[6:7], 0x3980000
	v_lshl_add_u64 v[92:93], v[12:13], 0, s[6:7]
	s_mov_b64 s[6:7], 0x39a0000
	v_mov_b32_e32 v73, v145
	v_lshl_add_u64 v[94:95], v[12:13], 0, s[6:7]
	v_lshl_add_u64 v[60:61], v[92:93], 0, v[72:73]
	v_lshl_add_u64 v[62:63], v[94:95], 0, v[72:73]
	s_mov_b64 s[98:99], 0x1000
	v_lshl_add_u64 v[180:181], v[60:61], 0, s[98:99]
	v_lshl_add_u64 v[182:183], v[62:63], 0, s[98:99]
	global_load_dwordx4 v[104:107], v[180:181], off offset:-4096
	global_load_dwordx4 v[108:111], v[182:183], off offset:-4096
	global_load_dwordx4 v[112:115], v[180:181], off offset:-4032
	global_load_dwordx4 v[116:119], v[182:183], off offset:-4032
	global_load_dwordx4 v[120:123], v[180:181], off offset:-2048
	global_load_dwordx4 v[124:127], v[182:183], off offset:-2048
	global_load_dwordx4 v[128:131], v[180:181], off offset:-1984
	global_load_dwordx4 v[132:135], v[182:183], off offset:-1984
	global_load_dwordx4 v[136:139], v[180:181], off
	global_load_dwordx4 v[140:143], v[182:183], off
	global_load_dwordx4 v[156:159], v[180:181], off offset:64
	global_load_dwordx4 v[160:163], v[182:183], off offset:64
	global_load_dwordx4 v[164:167], v[180:181], off offset:2048
	global_load_dwordx4 v[168:171], v[182:183], off offset:2048
	global_load_dwordx4 v[172:175], v[180:181], off offset:2112
	global_load_dwordx4 v[176:179], v[182:183], off offset:2112
	v_readlane_b32 s36, v254, 22
	v_readlane_b32 s40, v254, 26
	v_readlane_b32 s41, v254, 27
	s_mov_b64 s[6:7], s[40:41]
	v_readlane_b32 s44, v254, 30
	v_readlane_b32 s45, v254, 31
	s_mov_b32 s27, 0x122e6000
	s_mov_b32 s28, 0xc1000000
	v_lshrrev_b32_e32 v98, 1, v75
	v_readlane_b32 s37, v254, 23
	v_readlane_b32 s38, v254, 24
	v_readlane_b32 s39, v254, 25
	v_readlane_b32 s42, v254, 28
	v_readlane_b32 s43, v254, 29
	v_readlane_b32 s46, v254, 32
	v_readlane_b32 s47, v254, 33
	v_readlane_b32 s48, v254, 34
	v_readlane_b32 s49, v254, 35
	v_readlane_b32 s50, v254, 36
	v_readlane_b32 s51, v254, 37
	s_waitcnt vmcnt(0) lgkmcnt(0)
	v_mfma_f32_16x16x32_bf16 v[12:15], v[104:107], v[8:11], 0
	v_mfma_f32_16x16x32_bf16 v[48:51], v[108:111], v[8:11], 0
	v_mfma_f32_16x16x32_bf16 v[68:71], v[112:115], v[84:87], v[12:15]
	v_mfma_f32_16x16x32_bf16 v[64:67], v[116:119], v[84:87], v[48:51]
	s_nop 4
	v_mfma_f32_16x16x32_bf16 v[12:15], v[120:123], v[8:11], 0
	v_mfma_f32_16x16x32_bf16 v[48:51], v[124:127], v[8:11], 0
	v_mfma_f32_16x16x32_bf16 v[60:63], v[128:131], v[84:87], v[12:15]
	s_nop 5
	v_or_b32_e32 v12, 0x1000, v72
	v_mov_b32_e32 v13, v145
	v_lshl_add_u64 v[52:53], v[92:93], 0, v[12:13]
	v_mfma_f32_16x16x32_bf16 v[56:59], v[132:135], v[84:87], v[48:51]
	v_lshl_add_u64 v[88:89], v[94:95], 0, v[12:13]
	s_nop 0
	s_nop 0
	s_nop 0
	v_mfma_f32_16x16x32_bf16 v[12:15], v[136:139], v[8:11], 0
	v_mfma_f32_16x16x32_bf16 v[48:51], v[140:143], v[8:11], 0
	v_mfma_f32_16x16x32_bf16 v[52:55], v[156:159], v[84:87], v[12:15]
	s_nop 5
	v_or_b32_e32 v12, 0x1800, v72
	v_mov_b32_e32 v13, v145
	v_lshl_add_u64 v[72:73], v[92:93], 0, v[12:13]
	v_mfma_f32_16x16x32_bf16 v[48:51], v[160:163], v[84:87], v[48:51]
	v_lshl_add_u64 v[92:93], v[94:95], 0, v[12:13]
	v_mfma_f32_16x16x32_bf16 v[12:15], v[164:167], v[8:11], 0
	v_mfma_f32_16x16x32_bf16 v[8:11], v[168:171], v[8:11], 0
	s_nop 0
	v_lshl_or_b32 v73, v76, 4, v83
	v_lshlrev_b32_e32 v72, 2, v97
	v_lshlrev_b32_e32 v83, 7, v73
	v_lshlrev_b32_e32 v102, 8, v73
	v_mov_b32_e32 v73, v145
	v_mfma_f32_16x16x32_bf16 v[12:15], v[172:175], v[84:87], v[12:15]
	v_mfma_f32_16x16x32_bf16 v[8:11], v[176:179], v[84:87], v[8:11]
	v_lshl_add_u64 v[86:87], v[72:73], 0, s[8:9]
	v_lshlrev_b64 v[90:91], 2, v[86:87]
	v_lshl_add_u64 v[86:87], s[6:7], 0, v[90:91]
	flat_load_dwordx4 v[86:89], v[86:87] offset:2048
	s_mov_b64 s[6:7], s[44:45]
	v_bfe_u32 v84, v96, 1, 1
	v_lshl_add_u64 v[90:91], s[6:7], 0, v[90:91]
	s_mov_b64 s[6:7], s[74:75]
	flat_load_dwordx4 v[90:93], v[90:91] offset:2048
	s_add_u32 s6, s6, s3
	s_addc_u32 s7, s7, 0
	v_lshl_add_u64 v[94:95], s[6:7], 0, v[144:145]
	v_add_co_u32_e32 v94, vcc, s27, v94
	v_and_b32_e32 v85, 8, v98
	s_nop 0
	v_addc_co_u32_e32 v95, vcc, 0, v95, vcc
	flat_load_dwordx4 v[94:97], v[94:95] offset:2048
	v_bitop3_b32 v98, v84, v98, 7 bitop3:0x78
	v_add_u32_e32 v85, s60, v85
	v_lshlrev_b32_e32 v98, 4, v98
	v_add3_u32 v98, v85, v98, v83
	ds_read_b64 v[98:99], v98
	s_waitcnt lgkmcnt(0)
	v_lshlrev_b32_e32 v100, 16, v98
	v_and_b32_e32 v101, 0xffff0000, v98
	v_lshlrev_b32_e32 v98, 16, v99
	v_and_b32_e32 v99, 0xffff0000, v99
	s_waitcnt vmcnt(0)
	v_add_f32_e32 v68, v68, v86
	v_add_f32_e32 v69, v69, v87
	v_mul_f32_e32 v68, 0xbfb8aa3b, v68
	v_mul_f32_e32 v69, 0xbfb8aa3b, v69
	v_exp_f32_e32 v68, v68
	v_exp_f32_e32 v69, v69
	v_add_f32_e32 v64, v64, v90
	v_add_f32_e32 v65, v65, v91
	v_add_f32_e32 v68, 1.0, v68
	v_add_f32_e32 v69, 1.0, v69
	v_rcp_f32_e32 v68, v68
	v_rcp_f32_e32 v69, v69
	v_add_f32_e32 v70, v70, v88
	v_add_f32_e32 v71, v71, v89
	v_mul_f32_e32 v70, 0xbfb8aa3b, v70
	v_pk_mul_f32 v[68:69], v[68:69], s[28:29] op_sel_hi:[1,0]
	v_mul_f32_e32 v71, 0xbfb8aa3b, v71
	v_pk_mul_f32 v[86:87], v[94:95], v[68:69]
	v_exp_f32_e32 v70, v70
	v_pk_add_f32 v[90:91], v[86:87], v[86:87]
	v_mul_f32_e32 v68, 0x3fb8aa3b, v86
	v_fmamk_f32 v69, v90, 0x3ab60b61, v195
	v_exp_f32_e32 v68, v68
	v_fmaak_f32 v69, v90, v69, 0x3d2aaaab
	v_fmaak_f32 v69, v90, v69, 0x3e2aaaab
	v_exp_f32_e32 v71, v71
	v_fma_f32 v69, v90, v69, 0.5
	v_fma_f32 v69, v90, v69, 1.0
	v_mul_f32_e64 v69, v69, -v90
	v_fma_f32 v86, -v68, v68, 1.0
	v_cmp_lt_f32_e64 s[6:7], s84, v90
	v_add_f32_e32 v70, 1.0, v70
	v_add_f32_e32 v71, 1.0, v71
	v_cndmask_b32_e64 v69, v86, v69, s[6:7]
	v_sqrt_f32_e32 v86, v69
	v_mul_f32_e32 v69, 0x3fb8aa3b, v87
	v_fmamk_f32 v87, v91, 0x3ab60b61, v195
	v_rcp_f32_e32 v70, v70
	v_rcp_f32_e32 v71, v71
	v_exp_f32_e32 v69, v69
	v_fmaak_f32 v87, v91, v87, 0x3d2aaaab
	v_fmaak_f32 v87, v91, v87, 0x3e2aaaab
	v_fma_f32 v87, v91, v87, 0.5
	v_fma_f32 v87, v91, v87, 1.0
	v_pk_mul_f32 v[70:71], v[70:71], s[28:29] op_sel_hi:[1,0]
	v_cmp_lt_f32_e32 vcc, s84, v91
	v_mul_f32_e64 v87, v87, -v91
	v_fma_f32 v90, -v69, v69, 1.0
	v_pk_mul_f32 v[88:89], v[96:97], v[70:71]
	v_cndmask_b32_e32 v87, v90, v87, vcc
	v_pk_add_f32 v[90:91], v[88:89], v[88:89]
	v_mul_f32_e32 v70, 0x3fb8aa3b, v88
	v_fmamk_f32 v71, v90, 0x3ab60b61, v195
	v_exp_f32_e32 v70, v70
	v_fmaak_f32 v71, v90, v71, 0x3d2aaaab
	v_fmaak_f32 v71, v90, v71, 0x3e2aaaab
	v_fma_f32 v71, v90, v71, 0.5
	v_fma_f32 v71, v90, v71, 1.0
	v_mul_f32_e64 v71, v71, -v90
	v_fma_f32 v88, -v70, v70, 1.0
	v_cmp_lt_f32_e64 s[6:7], s84, v90
	v_add_f32_e32 v66, v66, v92
	v_add_f32_e32 v67, v67, v93
	v_cndmask_b32_e64 v71, v88, v71, s[6:7]
	v_sqrt_f32_e32 v88, v71
	v_mul_f32_e32 v71, 0x3fb8aa3b, v89
	v_fmamk_f32 v89, v91, 0x3ab60b61, v195
	v_mul_f32_e32 v64, 0xbfb8aa3b, v64
	v_mul_f32_e32 v65, 0xbfb8aa3b, v65
	v_mul_f32_e32 v66, 0xbfb8aa3b, v66
	v_mul_f32_e32 v67, 0xbfb8aa3b, v67
	v_exp_f32_e32 v71, v71
	v_fmaak_f32 v89, v91, v89, 0x3d2aaaab
	v_exp_f32_e32 v64, v64
	v_exp_f32_e32 v65, v65
	v_exp_f32_e32 v66, v66
	v_exp_f32_e32 v67, v67
	v_fmaak_f32 v89, v91, v89, 0x3e2aaaab
	v_fma_f32 v89, v91, v89, 0.5
	v_fma_f32 v89, v91, v89, 1.0
	v_cmp_lt_f32_e32 vcc, s84, v91
	v_mul_f32_e64 v89, v89, -v91
	v_fma_f32 v90, -v71, v71, 1.0
	v_add_f32_e32 v64, 1.0, v64
	v_add_f32_e32 v65, 1.0, v65
	v_add_f32_e32 v66, 1.0, v66
	v_add_f32_e32 v67, 1.0, v67
	v_cndmask_b32_e32 v89, v90, v89, vcc
	v_rcp_f32_e32 v64, v64
	v_rcp_f32_e32 v65, v65
	v_sqrt_f32_e32 v87, v87
	v_rcp_f32_e32 v66, v66
	v_rcp_f32_e32 v67, v67
	v_sqrt_f32_e32 v89, v89
	v_pk_mul_f32 v[64:65], v[64:65], v[86:87]
	s_mov_b64 s[6:7], s[40:41]
	v_pk_mul_f32 v[86:87], v[64:65], v[100:101]
	v_pk_mul_f32 v[66:67], v[66:67], v[88:89]
	v_lshl_add_u64 v[64:65], v[72:73], 0, s[12:13]
	v_pk_mul_f32 v[88:89], v[66:67], v[98:99]
	v_add3_u32 v66, s60, v102, v144
	ds_write_b128 v66, v[68:71] offset:8192
	ds_write_b128 v66, v[86:89] offset:24576
	v_lshlrev_b64 v[64:65], 2, v[64:65]
	v_lshl_add_u64 v[68:69], s[6:7], 0, v[64:65]
	s_mov_b64 s[6:7], s[44:45]
	flat_load_dwordx4 v[68:71], v[68:69] offset:64
	v_bitop3_b32 v67, v84, v77, 2 bitop3:0x36
	v_lshl_add_u64 v[72:73], s[6:7], 0, v[64:65]
	flat_load_dwordx4 v[86:89], v[72:73] offset:64
	s_mov_b64 s[6:7], s[74:75]
	s_add_u32 s6, s6, s3
	s_addc_u32 s7, s7, 0
	v_lshl_add_u64 v[72:73], s[6:7], 0, v[144:145]
	v_add_co_u32_e32 v72, vcc, s27, v72
	v_lshlrev_b32_e32 v67, 4, v67
	s_nop 0
	v_addc_co_u32_e32 v73, vcc, 0, v73, vcc
	flat_load_dwordx4 v[90:93], v[72:73] offset:2112
	v_add3_u32 v67, v85, v67, v83
	ds_read_b64 v[72:73], v67
	s_waitcnt lgkmcnt(0)
	v_lshlrev_b32_e32 v94, 16, v72
	v_and_b32_e32 v95, 0xffff0000, v72
	v_lshlrev_b32_e32 v72, 16, v73
	v_and_b32_e32 v73, 0xffff0000, v73
	s_waitcnt vmcnt(0)
	v_add_f32_e32 v60, v60, v68
	v_mul_f32_e32 v60, 0xbfb8aa3b, v60
	v_exp_f32_e32 v60, v60
	v_add_f32_e32 v62, v62, v70
	v_add_f32_e32 v56, v56, v86
	v_mul_f32_e32 v56, 0xbfb8aa3b, v56
	v_exp_f32_e32 v56, v56
	v_add_f32_e32 v58, v58, v88
	v_mul_f32_e32 v58, 0xbfb8aa3b, v58
	v_exp_f32_e32 v58, v58
	v_add_f32_e32 v56, 1.0, v56
	v_rcp_f32_e32 v68, v56
	v_add_f32_e32 v56, v61, v69
	v_mul_f32_e32 v56, 0xbfb8aa3b, v56
	v_exp_f32_e32 v56, v56
	v_add_f32_e32 v60, 1.0, v60
	v_rcp_f32_e32 v60, v60
	v_add_f32_e32 v58, 1.0, v58
	v_add_f32_e32 v56, 1.0, v56
	v_rcp_f32_e32 v61, v56
	v_add_f32_e32 v56, v57, v87
	v_mul_f32_e32 v56, 0xbfb8aa3b, v56
	v_exp_f32_e32 v56, v56
	v_rcp_f32_e32 v70, v58
	v_add_f32_e32 v58, v63, v71
	v_mul_f32_e32 v58, 0xbfb8aa3b, v58
	v_add_f32_e32 v56, 1.0, v56
	v_rcp_f32_e32 v69, v56
	v_pk_mul_f32 v[56:57], v[60:61], s[28:29] op_sel_hi:[1,0]
	v_exp_f32_e32 v58, v58
	v_pk_mul_f32 v[60:61], v[90:91], v[56:57]
	v_mul_f32_e32 v62, 0xbfb8aa3b, v62
	v_pk_add_f32 v[86:87], v[60:61], v[60:61]
	v_mul_f32_e32 v56, 0x3fb8aa3b, v60
	v_fmamk_f32 v57, v86, 0x3ab60b61, v195
	v_exp_f32_e32 v56, v56
	v_fmaak_f32 v57, v86, v57, 0x3d2aaaab
	v_exp_f32_e32 v62, v62
	v_fmaak_f32 v57, v86, v57, 0x3e2aaaab
	v_add_f32_e32 v58, 1.0, v58
	v_fma_f32 v57, v86, v57, 0.5
	v_rcp_f32_e32 v63, v58
	v_add_f32_e32 v58, v59, v89
	v_fma_f32 v57, v86, v57, 1.0
	v_mul_f32_e32 v58, 0xbfb8aa3b, v58
	v_mul_f32_e64 v57, v57, -v86
	v_fma_f32 v60, -v56, v56, 1.0
	v_cmp_lt_f32_e64 s[6:7], s84, v86
	v_add_f32_e32 v62, 1.0, v62
	v_exp_f32_e32 v58, v58
	v_cndmask_b32_e64 v57, v60, v57, s[6:7]
	v_rcp_f32_e32 v62, v62
	v_sqrt_f32_e32 v60, v57
	v_mul_f32_e32 v57, 0x3fb8aa3b, v61
	v_fmamk_f32 v61, v87, 0x3ab60b61, v195
	v_fmaak_f32 v61, v87, v61, 0x3d2aaaab
	v_fmaak_f32 v61, v87, v61, 0x3e2aaaab
	v_add_f32_e32 v58, 1.0, v58
	v_fma_f32 v61, v87, v61, 0.5
	v_rcp_f32_e32 v71, v58
	v_pk_mul_f32 v[58:59], v[62:63], s[28:29] op_sel_hi:[1,0]
	v_fma_f32 v61, v87, v61, 1.0
	v_pk_mul_f32 v[62:63], v[92:93], v[58:59]
	v_cmp_lt_f32_e32 vcc, s84, v87
	v_mul_f32_e64 v61, v61, -v87
	v_pk_add_f32 v[86:87], v[62:63], v[62:63]
	v_mul_f32_e32 v58, 0x3fb8aa3b, v62
	v_fmamk_f32 v59, v86, 0x3ab60b61, v195
	v_exp_f32_e32 v58, v58
	v_fmaak_f32 v59, v86, v59, 0x3d2aaaab
	v_fmaak_f32 v59, v86, v59, 0x3e2aaaab
	v_fma_f32 v59, v86, v59, 0.5
	v_fma_f32 v59, v86, v59, 1.0
	v_mul_f32_e64 v59, v59, -v86
	v_fma_f32 v62, -v58, v58, 1.0
	v_cmp_lt_f32_e64 s[6:7], s84, v86
	v_exp_f32_e32 v57, v57
	s_nop 0
	v_cndmask_b32_e64 v59, v62, v59, s[6:7]
	v_sqrt_f32_e32 v62, v59
	v_mul_f32_e32 v59, 0x3fb8aa3b, v63
	v_fmamk_f32 v63, v87, 0x3ab60b61, v195
	v_exp_f32_e32 v59, v59
	v_fmaak_f32 v63, v87, v63, 0x3d2aaaab
	v_fmaak_f32 v63, v87, v63, 0x3e2aaaab
	v_fma_f32 v63, v87, v63, 0.5
	v_fma_f32 v67, -v57, v57, 1.0
	v_fma_f32 v63, v87, v63, 1.0
	v_cndmask_b32_e32 v61, v67, v61, vcc
	v_cmp_lt_f32_e32 vcc, s84, v87
	v_mul_f32_e64 v63, v63, -v87
	v_fma_f32 v67, -v59, v59, 1.0
	v_cndmask_b32_e32 v63, v67, v63, vcc
	v_sqrt_f32_e32 v61, v61
	v_sqrt_f32_e32 v63, v63
	s_mov_b64 s[6:7], s[40:41]
	v_bitop3_b32 v67, v84, v77, 4 bitop3:0x36
	v_pk_mul_f32 v[60:61], v[68:69], v[60:61]
	v_pk_mul_f32 v[62:63], v[70:71], v[62:63]
	v_pk_mul_f32 v[60:61], v[60:61], v[94:95]
	v_pk_mul_f32 v[62:63], v[62:63], v[72:73]
	ds_write_b128 v66, v[56:59] offset:8256
	ds_write_b128 v66, v[60:63] offset:24640
	v_lshlrev_b32_e32 v67, 4, v67
	v_lshl_add_u64 v[56:57], s[6:7], 0, v[64:65]
	s_mov_b64 s[6:7], s[44:45]
	flat_load_dwordx4 v[56:59], v[56:57] offset:128
	v_add3_u32 v67, v85, v67, v83
	v_lshl_add_u64 v[60:61], s[6:7], 0, v[64:65]
	flat_load_dwordx4 v[60:63], v[60:61] offset:128
	s_mov_b64 s[6:7], s[74:75]
	s_add_u32 s6, s6, s3
	s_addc_u32 s7, s7, 0
	v_lshl_add_u64 v[68:69], s[6:7], 0, v[144:145]
	v_add_co_u32_e32 v68, vcc, s27, v68
	ds_read_b64 v[72:73], v67
	s_nop 0
	v_addc_co_u32_e32 v69, vcc, 0, v69, vcc
	flat_load_dwordx4 v[68:71], v[68:69] offset:2176
	s_waitcnt lgkmcnt(0)
	v_lshlrev_b32_e32 v86, 16, v72
	v_and_b32_e32 v87, 0xffff0000, v72
	v_lshlrev_b32_e32 v72, 16, v73
	v_and_b32_e32 v73, 0xffff0000, v73
	s_waitcnt vmcnt(0)
	v_add_f32_e32 v52, v52, v56
	v_mul_f32_e32 v52, 0xbfb8aa3b, v52
	v_exp_f32_e32 v52, v52
	v_add_f32_e32 v54, v54, v58
	v_add_f32_e32 v48, v48, v60
	v_mul_f32_e32 v48, 0xbfb8aa3b, v48
	v_exp_f32_e32 v48, v48
	v_add_f32_e32 v50, v50, v62
	v_mul_f32_e32 v50, 0xbfb8aa3b, v50
	v_add_f32_e32 v52, 1.0, v52
	v_add_f32_e32 v48, 1.0, v48
	v_rcp_f32_e32 v56, v48
	v_add_f32_e32 v48, v53, v57
	v_mul_f32_e32 v48, 0xbfb8aa3b, v48
	v_exp_f32_e32 v48, v48
	v_exp_f32_e32 v50, v50
	v_rcp_f32_e32 v52, v52
	v_mul_f32_e32 v54, 0xbfb8aa3b, v54
	v_add_f32_e32 v48, 1.0, v48
	v_rcp_f32_e32 v53, v48
	v_add_f32_e32 v48, v49, v61
	v_mul_f32_e32 v48, 0xbfb8aa3b, v48
	v_exp_f32_e32 v48, v48
	v_add_f32_e32 v50, 1.0, v50
	v_rcp_f32_e32 v58, v50
	v_add_f32_e32 v50, v55, v59
	v_add_f32_e32 v48, 1.0, v48
	v_rcp_f32_e32 v57, v48
	v_pk_mul_f32 v[48:49], v[52:53], s[28:29] op_sel_hi:[1,0]
	v_mul_f32_e32 v50, 0xbfb8aa3b, v50
	v_pk_mul_f32 v[52:53], v[68:69], v[48:49]
	v_exp_f32_e32 v50, v50
	v_pk_add_f32 v[60:61], v[52:53], v[52:53]
	v_mul_f32_e32 v48, 0x3fb8aa3b, v52
	v_fmamk_f32 v49, v60, 0x3ab60b61, v195
	v_exp_f32_e32 v48, v48
	v_fmaak_f32 v49, v60, v49, 0x3d2aaaab
	v_fmaak_f32 v49, v60, v49, 0x3e2aaaab
	v_exp_f32_e32 v54, v54
	v_fma_f32 v49, v60, v49, 0.5
	v_add_f32_e32 v50, 1.0, v50
	v_fma_f32 v49, v60, v49, 1.0
	v_rcp_f32_e32 v55, v50
	v_add_f32_e32 v50, v51, v63
	v_mul_f32_e64 v49, v49, -v60
	v_fma_f32 v52, -v48, v48, 1.0
	v_cmp_lt_f32_e64 s[6:7], s84, v60
	v_mul_f32_e32 v50, 0xbfb8aa3b, v50
	v_add_f32_e32 v54, 1.0, v54
	v_cndmask_b32_e64 v49, v52, v49, s[6:7]
	v_exp_f32_e32 v50, v50
	v_sqrt_f32_e32 v52, v49
	v_mul_f32_e32 v49, 0x3fb8aa3b, v53
	v_fmamk_f32 v53, v61, 0x3ab60b61, v195
	v_rcp_f32_e32 v54, v54
	v_exp_f32_e32 v49, v49
	v_fmaak_f32 v53, v61, v53, 0x3d2aaaab
	v_fmaak_f32 v53, v61, v53, 0x3e2aaaab
	v_fma_f32 v53, v61, v53, 0.5
	v_add_f32_e32 v50, 1.0, v50
	v_fma_f32 v53, v61, v53, 1.0
	v_rcp_f32_e32 v59, v50
	v_pk_mul_f32 v[50:51], v[54:55], s[28:29] op_sel_hi:[1,0]
	v_cmp_lt_f32_e32 vcc, s84, v61
	v_mul_f32_e64 v53, v53, -v61
	v_fma_f32 v60, -v49, v49, 1.0
	v_pk_mul_f32 v[54:55], v[70:71], v[50:51]
	v_cndmask_b32_e32 v53, v60, v53, vcc
	v_pk_add_f32 v[60:61], v[54:55], v[54:55]
	v_mul_f32_e32 v50, 0x3fb8aa3b, v54
	v_fmamk_f32 v51, v60, 0x3ab60b61, v195
	v_exp_f32_e32 v50, v50
	v_fmaak_f32 v51, v60, v51, 0x3d2aaaab
	v_fmaak_f32 v51, v60, v51, 0x3e2aaaab
	v_fma_f32 v51, v60, v51, 0.5
	v_fma_f32 v51, v60, v51, 1.0
	v_mul_f32_e64 v51, v51, -v60
	v_fma_f32 v54, -v50, v50, 1.0
	v_cmp_lt_f32_e64 s[6:7], s84, v60
	v_cmp_lt_f32_e32 vcc, s84, v61
	v_sqrt_f32_e32 v53, v53
	v_cndmask_b32_e64 v51, v54, v51, s[6:7]
	v_sqrt_f32_e32 v54, v51
	v_mul_f32_e32 v51, 0x3fb8aa3b, v55
	v_fmamk_f32 v55, v61, 0x3ab60b61, v195
	v_exp_f32_e32 v51, v51
	v_fmaak_f32 v55, v61, v55, 0x3d2aaaab
	v_fmaak_f32 v55, v61, v55, 0x3e2aaaab
	v_fma_f32 v55, v61, v55, 0.5
	v_fma_f32 v55, v61, v55, 1.0
	v_mul_f32_e64 v55, v55, -v61
	v_fma_f32 v60, -v51, v51, 1.0
	v_cndmask_b32_e32 v55, v60, v55, vcc
	v_sqrt_f32_e32 v55, v55
	v_pk_mul_f32 v[52:53], v[56:57], v[52:53]
	s_mov_b64 s[6:7], s[40:41]
	v_pk_mul_f32 v[52:53], v[52:53], v[86:87]
	v_pk_mul_f32 v[54:55], v[58:59], v[54:55]
	v_bitop3_b32 v60, v84, v77, 6 bitop3:0x36
	v_pk_mul_f32 v[54:55], v[54:55], v[72:73]
	ds_write_b128 v66, v[48:51] offset:8320
	ds_write_b128 v66, v[52:55] offset:24704
	v_lshlrev_b32_e32 v60, 4, v60
	v_lshl_add_u64 v[48:49], s[6:7], 0, v[64:65]
	s_mov_b64 s[6:7], s[44:45]
	flat_load_dwordx4 v[48:51], v[48:49] offset:192
	v_add3_u32 v60, v85, v60, v83
	v_lshl_add_u64 v[52:53], s[6:7], 0, v[64:65]
	flat_load_dwordx4 v[52:55], v[52:53] offset:192
	s_mov_b64 s[6:7], s[74:75]
	s_add_u32 s6, s6, s3
	s_addc_u32 s7, s7, 0
	v_lshl_add_u64 v[56:57], s[6:7], 0, v[144:145]
	v_add_co_u32_e32 v56, vcc, s27, v56
	ds_read_b64 v[60:61], v60
	s_nop 0
	v_addc_co_u32_e32 v57, vcc, 0, v57, vcc
	flat_load_dwordx4 v[56:59], v[56:57] offset:2240
	s_waitcnt lgkmcnt(0)
	v_lshlrev_b32_e32 v62, 16, v60
	v_and_b32_e32 v63, 0xffff0000, v60
	v_lshlrev_b32_e32 v60, 16, v61
	v_and_b32_e32 v61, 0xffff0000, v61
	s_waitcnt vmcnt(0)
	v_add_f32_e32 v12, v12, v48
	v_mul_f32_e32 v12, 0xbfb8aa3b, v12
	v_exp_f32_e32 v12, v12
	v_add_f32_e32 v14, v14, v50
	v_add_f32_e32 v8, v8, v52
	v_mul_f32_e32 v8, 0xbfb8aa3b, v8
	v_exp_f32_e32 v8, v8
	v_add_f32_e32 v10, v10, v54
	v_mul_f32_e32 v10, 0xbfb8aa3b, v10
	v_add_f32_e32 v12, 1.0, v12
	v_add_f32_e32 v8, 1.0, v8
	v_rcp_f32_e32 v48, v8
	v_add_f32_e32 v8, v13, v49
	v_mul_f32_e32 v8, 0xbfb8aa3b, v8
	v_exp_f32_e32 v8, v8
	v_exp_f32_e32 v10, v10
	v_rcp_f32_e32 v12, v12
	v_mul_f32_e32 v14, 0xbfb8aa3b, v14
	v_add_f32_e32 v8, 1.0, v8
	v_rcp_f32_e32 v13, v8
	v_add_f32_e32 v8, v9, v53
	v_mul_f32_e32 v8, 0xbfb8aa3b, v8
	v_exp_f32_e32 v8, v8
	v_add_f32_e32 v10, 1.0, v10
	v_rcp_f32_e32 v50, v10
	v_add_f32_e32 v10, v15, v51
	v_add_f32_e32 v8, 1.0, v8
	v_rcp_f32_e32 v49, v8
	v_pk_mul_f32 v[8:9], v[12:13], s[28:29] op_sel_hi:[1,0]
	v_mul_f32_e32 v10, 0xbfb8aa3b, v10
	v_pk_mul_f32 v[12:13], v[56:57], v[8:9]
	v_exp_f32_e32 v10, v10
	v_pk_add_f32 v[52:53], v[12:13], v[12:13]
	v_mul_f32_e32 v8, 0x3fb8aa3b, v12
	v_fmamk_f32 v9, v52, 0x3ab60b61, v195
	v_exp_f32_e32 v8, v8
	v_fmaak_f32 v9, v52, v9, 0x3d2aaaab
	v_fmaak_f32 v9, v52, v9, 0x3e2aaaab
	v_exp_f32_e32 v14, v14
	v_fma_f32 v9, v52, v9, 0.5
	v_add_f32_e32 v10, 1.0, v10
	v_fma_f32 v9, v52, v9, 1.0
	v_rcp_f32_e32 v15, v10
	v_add_f32_e32 v10, v11, v55
	v_mul_f32_e64 v9, v9, -v52
	v_fma_f32 v12, -v8, v8, 1.0
	v_cmp_lt_f32_e64 s[6:7], s84, v52
	v_mul_f32_e32 v10, 0xbfb8aa3b, v10
	v_add_f32_e32 v14, 1.0, v14
	v_cndmask_b32_e64 v9, v12, v9, s[6:7]
	v_exp_f32_e32 v10, v10
	v_sqrt_f32_e32 v12, v9
	v_mul_f32_e32 v9, 0x3fb8aa3b, v13
	v_fmamk_f32 v13, v53, 0x3ab60b61, v195
	v_rcp_f32_e32 v14, v14
	v_exp_f32_e32 v9, v9
	v_fmaak_f32 v13, v53, v13, 0x3d2aaaab
	v_fmaak_f32 v13, v53, v13, 0x3e2aaaab
	v_fma_f32 v13, v53, v13, 0.5
	v_add_f32_e32 v10, 1.0, v10
	v_fma_f32 v13, v53, v13, 1.0
	v_rcp_f32_e32 v51, v10
	v_pk_mul_f32 v[10:11], v[14:15], s[28:29] op_sel_hi:[1,0]
	v_cmp_lt_f32_e32 vcc, s84, v53
	v_mul_f32_e64 v13, v13, -v53
	v_fma_f32 v52, -v9, v9, 1.0
	v_pk_mul_f32 v[14:15], v[58:59], v[10:11]
	v_cndmask_b32_e32 v13, v52, v13, vcc
	v_pk_add_f32 v[52:53], v[14:15], v[14:15]
	v_mul_f32_e32 v10, 0x3fb8aa3b, v14
	v_fmamk_f32 v11, v52, 0x3ab60b61, v195
	v_exp_f32_e32 v10, v10
	v_fmaak_f32 v11, v52, v11, 0x3d2aaaab
	v_fmaak_f32 v11, v52, v11, 0x3e2aaaab
	v_fma_f32 v11, v52, v11, 0.5
	v_fma_f32 v11, v52, v11, 1.0
	v_mul_f32_e64 v11, v11, -v52
	v_fma_f32 v14, -v10, v10, 1.0
	v_cmp_lt_f32_e64 s[6:7], s84, v52
	v_cmp_lt_f32_e32 vcc, s84, v53
	v_sqrt_f32_e32 v13, v13
	v_cndmask_b32_e64 v11, v14, v11, s[6:7]
	v_sqrt_f32_e32 v14, v11
	v_mul_f32_e32 v11, 0x3fb8aa3b, v15
	v_fmamk_f32 v15, v53, 0x3ab60b61, v195
	v_exp_f32_e32 v11, v11
	v_fmaak_f32 v15, v53, v15, 0x3d2aaaab
	v_fmaak_f32 v15, v53, v15, 0x3e2aaaab
	v_fma_f32 v15, v53, v15, 0.5
	v_fma_f32 v15, v53, v15, 1.0
	v_mul_f32_e64 v15, v15, -v53
	v_fma_f32 v52, -v11, v11, 1.0
	v_cndmask_b32_e32 v15, v52, v15, vcc
	v_sqrt_f32_e32 v15, v15
	v_pk_mul_f32 v[12:13], v[48:49], v[12:13]
	v_cmp_gt_u32_e32 vcc, 64, v75
	v_pk_mul_f32 v[12:13], v[12:13], v[62:63]
	v_pk_mul_f32 v[14:15], v[50:51], v[14:15]
	s_nop 0
	v_pk_mul_f32 v[14:15], v[14:15], v[60:61]
	ds_write_b128 v66, v[8:11] offset:8384
	ds_write_b128 v66, v[12:15] offset:24768
	v_and_b32_e32 v8, 63, v74
	v_lshlrev_b32_e32 v9, 2, v8
	v_lshl_or_b32 v9, v76, 12, v9
	v_add_u32_e32 v9, s60, v9
	s_waitcnt lgkmcnt(0)
	s_barrier
	ds_read2st64_b32 v[10:11], v9 offset0:46 offset1:47
	ds_read2st64_b32 v[12:13], v9 offset0:110 offset1:111
	ds_read2st64_b32 v[14:15], v9 offset0:44 offset1:45
	ds_read2st64_b32 v[48:49], v9 offset0:108 offset1:109
	s_waitcnt lgkmcnt(2)
	v_fma_f32 v13, 0, v11, v13
	v_fmac_f32_e32 v12, v13, v10
	v_mul_f32_e32 v10, v11, v10
	s_waitcnt lgkmcnt(0)
	v_fma_f32 v11, v12, v15, v49
	ds_read2st64_b32 v[12:13], v9 offset0:42 offset1:43
	ds_read2st64_b32 v[50:51], v9 offset0:106 offset1:107
	v_fmac_f32_e32 v48, v11, v14
	v_mov_b32_e32 v58, v15
	s_waitcnt lgkmcnt(0)
	v_fma_f32 v11, v48, v13, v51
	ds_read2st64_b32 v[48:49], v9 offset0:40 offset1:41
	ds_read2st64_b32 v[52:53], v9 offset0:104 offset1:105
	v_fmac_f32_e32 v50, v11, v12
	s_waitcnt lgkmcnt(1)
	v_mov_b32_e32 v62, v49
	s_waitcnt lgkmcnt(0)
	v_fma_f32 v11, v50, v49, v53
	ds_read2st64_b32 v[50:51], v9 offset0:38 offset1:39
	ds_read2st64_b32 v[54:55], v9 offset0:102 offset1:103
	v_fmac_f32_e32 v52, v11, v48
	v_mov_b32_e32 v64, v49
	s_waitcnt lgkmcnt(1)
	v_mov_b32_e32 v59, v50
	s_waitcnt lgkmcnt(0)
	v_fmac_f32_e32 v55, v52, v51
	ds_read2st64_b32 v[52:53], v9 offset0:36 offset1:37
	ds_read2st64_b32 v[56:57], v9 offset0:100 offset1:101
	v_mov_b32_e32 v11, v55
	v_mul_f32_e32 v55, v10, v15
	v_mov_b32_e32 v15, v54
	v_pk_fma_f32 v[10:11], v[10:11], v[58:59], v[14:15]
	v_mul_f32_e32 v54, v55, v14
	v_mov_b32_e32 v55, v11
	v_mov_b32_e32 v10, v13
	s_waitcnt lgkmcnt(1)
	v_mov_b32_e32 v11, v53
	v_pk_mul_f32 v[14:15], v[54:55], v[10:11]
	s_waitcnt lgkmcnt(0)
	v_mov_b32_e32 v13, v57
	v_pk_mul_f32 v[14:15], v[14:15], v[12:13]
	v_pk_fma_f32 v[10:11], v[54:55], v[10:11], v[12:13]
	ds_read2st64_b32 v[12:13], v9 offset0:34 offset1:35
	ds_read2st64_b32 v[54:55], v9 offset0:98 offset1:99
	ds_read2st64_b32 v[58:59], v9 offset0:32 offset1:33
	ds_read2st64_b32 v[60:61], v9 offset0:96 offset1:97
	v_mov_b32_e32 v10, v14
	v_mov_b32_e32 v65, v52
	v_pk_mul_f32 v[14:15], v[14:15], v[62:63]
	v_mov_b32_e32 v49, v56
	v_pk_mul_f32 v[14:15], v[14:15], v[48:49]
	v_pk_fma_f32 v[10:11], v[10:11], v[64:65], v[48:49]
	v_and_b32_e32 v57, 0x1fffffc0, v75
	v_mov_b32_e32 v15, v11
	v_mov_b32_e32 v10, v51
	s_waitcnt lgkmcnt(3)
	v_mov_b32_e32 v11, v13
	v_pk_mul_f32 v[48:49], v[14:15], v[10:11]
	s_waitcnt lgkmcnt(2)
	v_mov_b32_e32 v51, v55
	v_pk_mul_f32 v[48:49], v[48:49], v[50:51]
	v_pk_fma_f32 v[10:11], v[14:15], v[10:11], v[50:51]
	v_mov_b32_e32 v14, v53
	v_mov_b32_e32 v10, v48
	v_mov_b32_e32 v50, v53
	v_mov_b32_e32 v51, v12
	v_pk_mul_f32 v[14:15], v[48:49], v[14:15]
	v_mov_b32_e32 v53, v54
	v_pk_mul_f32 v[14:15], v[14:15], v[52:53]
	v_pk_fma_f32 v[10:11], v[10:11], v[50:51], v[52:53]
	v_lshl_add_u32 v9, v8, 3, s60
	v_mov_b32_e32 v15, v11
	v_mov_b32_e32 v10, v13
	s_waitcnt lgkmcnt(1)
	v_mov_b32_e32 v11, v59
	v_pk_mul_f32 v[48:49], v[14:15], v[10:11]
	s_waitcnt lgkmcnt(0)
	v_mov_b32_e32 v13, v61
	v_pk_mul_f32 v[48:49], v[48:49], v[12:13]
	v_pk_fma_f32 v[10:11], v[14:15], v[10:11], v[12:13]
	v_mov_b32_e32 v12, v59
	v_mov_b32_e32 v10, v48
	v_mov_b32_e32 v14, v59
	v_mov_b32_e32 v15, v58
	v_pk_mul_f32 v[12:13], v[48:49], v[12:13]
	v_mov_b32_e32 v59, v60
	v_pk_mul_f32 v[12:13], v[12:13], v[58:59]
	v_pk_fma_f32 v[10:11], v[10:11], v[14:15], v[58:59]
	v_lshl_add_u32 v57, v57, 3, v9
	v_mov_b32_e32 v13, v11
	ds_write_b64 v57, v[12:13] offset:40960
	s_waitcnt lgkmcnt(0)
	s_barrier
	s_and_saveexec_b64 s[6:7], vcc
	s_cbranch_execz .LBB0_382
	s_lshl_b32 s26, s26, 7
	ds_read_b64 v[14:15], v9 offset:42496
	v_lshl_or_b32 v10, v74, 3, v196
	s_or_b32 s25, s26, s25
	v_add_u32_e32 v10, s60, v10
	s_or_b32 s26, s25, 64
	ds_read_b64 v[48:49], v10 offset:42496
	ds_read2st64_b64 v[10:13], v9 offset0:80 offset1:81
	s_ashr_i32 s27, s26, 31
	s_lshl_b64 s[26:27], s[26:27], 12
	s_mov_b64 s[28:29], s[74:75]
	s_add_u32 s25, s28, s26
	s_waitcnt lgkmcnt(2)
	v_fma_f32 v9, 0, v14, v15
	s_addc_u32 s27, s29, s27
	s_lshl_b32 s26, s23, 3
	s_waitcnt lgkmcnt(1)
	v_fmac_f32_e32 v49, v9, v48
	s_add_u32 s26, s25, s26
	v_mul_f32_e32 v14, v14, v48
	s_waitcnt lgkmcnt(0)
	v_fma_f32 v15, v49, v12, v13
	v_mov_b32_e32 v13, v10
	s_addc_u32 s27, s27, 0
	v_lshlrev_b32_e32 v144, 3, v8
	v_pk_mul_f32 v[48:49], v[14:15], v[12:13]
	v_lshl_add_u64 v[8:9], s[26:27], 0, v[144:145]
	v_pk_mul_f32 v[48:49], v[48:49], v[10:11]
	v_pk_fma_f32 v[10:11], v[14:15], v[12:13], v[10:11]
	v_add_co_u32_e32 v8, vcc, 0x115e0000, v8
	v_mov_b32_e32 v49, v11
	s_nop 0
	v_addc_co_u32_e32 v9, vcc, 0, v9, vcc
	flat_store_dwordx2 v[8:9], v[48:49]
	s_branch .LBB0_382

.LBB0_413:
	s_ashr_i32 s0, s57, 5
	s_mul_hi_i32 s3, s0, 0xb21642c9
	s_add_i32 s3, s3, s0
	s_lshr_b32 s6, s3, 31
	s_ashr_i32 s7, s3, 4
	s_add_i32 s7, s7, s6
	s_lshl_b32 s3, s57, 3
	s_and_b32 s3, s3, 56
	s_lshl_b32 s61, s7, 2
	s_bfe_u32 s2, s57, 0x20003
	s_add_i32 s3, s61, s3
	s_or_b32 s6, s3, s2
	s_cmp_eq_u32 s6, s56
	s_cbranch_scc1 .LBB0_417
	s_mov_b64 s[2:3], s[74:75]
	s_add_u32 s24, s2, s30
	s_addc_u32 s25, s3, s31
	s_lshl_b32 s2, s6, 8
	s_ashr_i32 s3, s2, 31
	s_waitcnt vmcnt(0) lgkmcnt(0)
	v_mov_b32_e32 v0, v190
	s_lshl_b64 s[2:3], s[2:3], 2
	s_add_u32 s2, s24, s2
	v_ashrrev_i32_e32 v1, 5, v0
	v_and_b32_e32 v2, -8, v1
	s_addc_u32 s3, s25, s3
	v_lshlrev_b32_sdwa v144, v203, v0 dst_sel:DWORD dst_unused:UNUSED_PAD src0_sel:DWORD src1_sel:BYTE_0
	v_lshl_add_u64 v[4:5], s[2:3], 0, v[144:145]
	s_mov_b64 s[2:3], 0x117e0000
	v_ashrrev_i32_e32 v3, 31, v2
	v_lshl_add_u64 v[4:5], v[4:5], 0, s[2:3]
	v_lshlrev_b64 v[6:7], 16, v[2:3]
	v_lshl_add_u64 v[8:9], v[4:5], 0, v[6:7]
	s_mov_b64 s[98:99], 0x10000
	v_lshl_add_u64 v[10:11], v[8:9], 0, s[98:99]
	v_lshl_add_u64 v[12:13], v[10:11], 0, s[98:99]
	v_lshl_add_u64 v[14:15], v[12:13], 0, s[98:99]
	v_lshl_add_u64 v[16:17], v[14:15], 0, s[98:99]
	v_lshl_add_u64 v[18:19], v[16:17], 0, s[98:99]
	v_lshl_add_u64 v[20:21], v[18:19], 0, s[98:99]
	v_lshl_add_u64 v[22:23], v[20:21], 0, s[98:99]
	global_load_dword v24, v[8:9], off
	global_load_dword v25, v[10:11], off
	global_load_dword v26, v[12:13], off
	global_load_dword v27, v[14:15], off
	global_load_dword v28, v[16:17], off
	global_load_dword v29, v[18:19], off
	global_load_dword v30, v[20:21], off
	global_load_dword v31, v[22:23], off
	v_cmp_gt_i32_e32 vcc, s71, v0
	s_waitcnt vmcnt(1)
	v_add_f32_e32 v3, 0, v24
	v_add_f32_e32 v3, v3, v25
	v_add_f32_e32 v3, v3, v26
	v_add_f32_e32 v3, v3, v27
	v_add_f32_e32 v3, v3, v28
	v_add_f32_e32 v6, v3, v29
	v_add_f32_e32 v6, v6, v30
	s_waitcnt lgkmcnt(0)
	s_barrier
	s_waitcnt vmcnt(0)
	v_add_f32_e32 v2, v6, v31
	v_lshl_add_u32 v1, v0, 2, v204
	ds_write_b32 v1, v2
	s_waitcnt lgkmcnt(0)
	s_barrier
	s_and_saveexec_b64 s[2:3], vcc
	s_cbranch_execz .LBB0_416
	ds_read2st64_b32 v[2:3], v1 offset1:4
	v_lshl_add_u32 v0, v0, 2, v205
	s_waitcnt lgkmcnt(0)
	v_add_f32_e32 v1, v2, v3
	v_fmamk_f32 v1, v1, 0x3a800000, v192
	v_mul_f32_e32 v2, 0x4b800000, v1
	v_cmp_gt_f32_e32 vcc, s58, v1
	s_nop 1
	v_cndmask_b32_e32 v1, v1, v2, vcc
	v_rsq_f32_e32 v1, v1
	s_nop 0
	v_mul_f32_e32 v2, 0x45800000, v1
	v_cndmask_b32_e32 v1, v1, v2, vcc
	ds_write_b32 v0, v1

.LBB0_663:
	s_cmp_eq_u32 s26, s68
	s_cselect_b64 s[2:3], -1, 0
	s_or_b64 s[2:3], s[56:57], s[2:3]
	s_and_b64 vcc, exec, s[2:3]
	s_cbranch_vccnz .LBB0_667
	s_lshl_b32 s2, s26, 8
	s_waitcnt vmcnt(0) lgkmcnt(0)
	v_mov_b32_e32 v0, v190
	s_ashr_i32 s3, s2, 31
	s_lshl_b64 s[2:3], s[2:3], 2
	v_ashrrev_i32_e32 v1, 5, v0
	v_and_b32_e32 v2, -8, v1
	s_add_u32 s2, s62, s2
	s_addc_u32 s3, s63, s3
	v_lshlrev_b32_sdwa v144, v203, v0 dst_sel:DWORD dst_unused:UNUSED_PAD src0_sel:DWORD src1_sel:BYTE_0
	v_ashrrev_i32_e32 v3, 31, v2
	v_lshl_add_u64 v[4:5], s[2:3], 0, v[144:145]
	v_lshlrev_b64 v[6:7], 16, v[2:3]
	v_lshl_add_u64 v[8:9], v[4:5], 0, v[6:7]
	s_mov_b64 s[98:99], 0x10000
	v_lshl_add_u64 v[10:11], v[8:9], 0, s[98:99]
	v_lshl_add_u64 v[12:13], v[10:11], 0, s[98:99]
	v_lshl_add_u64 v[14:15], v[12:13], 0, s[98:99]
	v_lshl_add_u64 v[16:17], v[14:15], 0, s[98:99]
	v_lshl_add_u64 v[18:19], v[16:17], 0, s[98:99]
	v_lshl_add_u64 v[20:21], v[18:19], 0, s[98:99]
	v_lshl_add_u64 v[22:23], v[20:21], 0, s[98:99]
	global_load_dword v24, v[8:9], off
	global_load_dword v25, v[10:11], off
	global_load_dword v26, v[12:13], off
	global_load_dword v27, v[14:15], off
	global_load_dword v28, v[16:17], off
	global_load_dword v29, v[18:19], off
	global_load_dword v30, v[20:21], off
	global_load_dword v31, v[22:23], off
	v_cmp_gt_i32_e32 vcc, s71, v0
	s_waitcnt vmcnt(1)
	v_add_f32_e32 v3, 0, v24
	v_add_f32_e32 v3, v3, v25
	v_add_f32_e32 v3, v3, v26
	v_add_f32_e32 v3, v3, v27
	v_add_f32_e32 v3, v3, v28
	v_add_f32_e32 v6, v3, v29
	v_add_f32_e32 v6, v6, v30
	s_waitcnt lgkmcnt(0)
	s_barrier
	s_waitcnt vmcnt(0)
	v_add_f32_e32 v2, v6, v31
	v_lshl_add_u32 v1, v0, 2, v204
	ds_write_b32 v1, v2
	s_waitcnt lgkmcnt(0)
	s_barrier
	s_and_saveexec_b64 s[2:3], vcc
	s_cbranch_execz .LBB0_666
	ds_read2st64_b32 v[2:3], v1 offset1:4
	v_lshl_add_u32 v0, v0, 2, v205
	s_waitcnt lgkmcnt(0)
	v_add_f32_e32 v1, v2, v3
	v_fmamk_f32 v1, v1, 0x3a800000, v192
	v_mul_f32_e32 v2, 0x4b800000, v1
	v_cmp_gt_f32_e32 vcc, s40, v1
	s_nop 1
	v_cndmask_b32_e32 v1, v1, v2, vcc
	v_rsq_f32_e32 v1, v1
	s_nop 0
	v_mul_f32_e32 v2, 0x45800000, v1
	v_cndmask_b32_e32 v1, v1, v2, vcc
	ds_write_b32 v0, v1
